# v4: + DSA indexer scoring loop software-pipelined (MFMA of step s+2 under VALU of step s), wave-private barriers removed in sparse-attention loop, DSA/DA items taken from a device-wide atomic queue (h
# speedup vs baseline: 1.0421x; 1.0421x over previous
; DI char* WS(const Params& P) { return P.ws + opaque0(); }
; DI void dsa_item(const Params& P, int layer, int b, int qt, char* mb, char* smem) {
;     ...
;   __syncthreads();
;   for (int i = tid; i < 4 * 129; i += 256) sbias[i] = ((const float*)(WS(P) + OFF_BIAS))[4 * 129 + i];
; DI void phase_mix1(const Params& P, int layer, int bid, int nb, char* smem) {
;     ...
;   for (int j = 0;; j++) {
;     const int idx = (j & 1) ? (j * nb + (nb - 1 - bid)) : (j * nb + bid);
;     if (j * nb >= 2048) break;
;     if (idx >= 2048) continue;
;     const int qt = 255 - (idx >> 3), b = idx & 7;
;     dsa_item(P, layer, b, qt, mb, smem);
.LBB0_3227:
	s_waitcnt vmcnt(0) lgkmcnt(0)
	s_barrier
	v_readlane_b32 s4, v237, 9
	v_readlane_b32 s5, v237, 10
	s_mov_b64 s[0:1], exec
	s_and_b64 s[4:5], s[0:1], s[4:5]
	s_mov_b64 exec, s[4:5]
	s_cbranch_execz .Lq_dsa0_skip
	v_readlane_b32 s4, v237, 0
	v_readlane_b32 s5, v237, 1
	s_add_u32 s4, s4, 0x5589140
	s_addc_u32 s5, s5, 0
	v_mov_b32_e32 v238, 0
	v_mov_b32_e32 v239, 1
	global_atomic_add v239, v238, v239, s[4:5] sc0
	v_mov_b32_e32 v238, 0x11ff8
	s_waitcnt vmcnt(0)
	ds_write_b32 v238, v239
.Lq_dsa0_skip:
	s_mov_b64 exec, s[0:1]
	s_waitcnt lgkmcnt(0)
	s_barrier
	v_mov_b32_e32 v238, 0x11ff8
	ds_read_b32 v238, v238
	s_waitcnt lgkmcnt(0)
	s_nop 0
	v_readfirstlane_b32 s6, v238
	s_cmpk_gt_i32 s6, 0x7ff
	s_mov_b32 s7, 5
	s_cbranch_scc1 .LBB0_4105
	v_mov_b32_e32 v68, v202
	s_movk_i32 s0, 0x203
	s_mov_b64 s[72:73], 0
	v_cmp_lt_i32_e32 vcc, s0, v68
	v_ashrrev_i32_e32 v69, 31, v68
	v_add_u32_e32 v131, 0xffffff00, v68
	v_lshlrev_b32_e32 v85, 2, v68
	s_waitcnt vmcnt(0) lgkmcnt(0)
	s_barrier
	s_and_saveexec_b64 s[0:1], vcc
	s_xor_b64 s[0:1], exec, s[0:1]
	v_add_u32_e32 v131, 0xffffff00, v68
	v_lshlrev_b32_e32 v85, 2, v68
	s_andn2_saveexec_b64 s[0:1], s[0:1]
	s_cbranch_execz .LBB0_3235
	v_readlane_b32 s4, v236, 28
	v_mov_b32_e32 v4, v131
	s_nop 0
	v_add_u32_e32 v1, s4, v85
	v_readlane_b32 s4, v236, 26
	v_readlane_b32 s5, v236, 27
	s_nop 1
	v_lshl_add_u64 v[2:3], v[68:69], 2, s[4:5]
	s_mov_b64 s[4:5], 0

; #define MFMA32(a, b, c) __builtin_amdgcn_mfma_f32_32x32x16_bf16((a), (b), (c), 0, 0, 0)
; DI f32x16 zero16() { f32x16 z; for (int i = 0; i < 16; i++) z[i] = 0.f; return z; }
; DI void dsa_item(const Params& P, int layer, int b, int qt, char* mb, char* smem) {
;     ...
; #pragma unroll 2
;       for (int hd = 0; hd < 8; hd++) {
;         const bf16x8 q0f = *(const bf16x8*)(sQi + r * 528 + hd * 64 + hh * 16);
;         const bf16x8 q1f = *(const bf16x8*)(sQi + r * 528 + hd * 64 + 32 + hh * 16);
;         const float w = sWi[hd * 32 + r];
;         f32x16 sa = MFMA32(kA0, q0f, zero16());
;         f32x16 sb = MFMA32(kB0, q0f, zero16());
;         sa = MFMA32(kA1, q1f, sa);
;         sb = MFMA32(kB1, q1f, sb);
; #pragma unroll
;         for (int i = 0; i < 16; i++) {
;           scA[i] += __int_as_float(max(__float_as_int(sa[i]), 0)) * w;
;           scB[i] += __int_as_float(max(__float_as_int(sb[i]), 0)) * w;
;         }
;       }
.LBB0_3246:
	v_add_u32_e32 v153, 0xffffff80, v148
	ds_read_b128 v[228:231], v147
	ds_read_b128 v[232:235], v147 offset:32
	ds_read_b32 v238, v153
	s_waitcnt lgkmcnt(2)
	v_mfma_f32_32x32x16_bf16 v[2:17], v[64:67], v[228:231], 0
	v_mfma_f32_32x32x16_bf16 v[18:33], v[56:59], v[228:231], 0
	s_waitcnt lgkmcnt(1)
	v_mfma_f32_32x32x16_bf16 v[2:17], v[60:63], v[232:235], v[2:17]
	v_mfma_f32_32x32x16_bf16 v[18:33], v[52:55], v[232:235], v[18:33]
	ds_read_b128 v[228:231], v147 offset:64
	ds_read_b128 v[232:235], v147 offset:96
	ds_read_b32 v239, v153 offset:128
	s_waitcnt lgkmcnt(1)
	v_mfma_f32_32x32x16_bf16 v[240:255], v[64:67], v[228:231], 0
	v_mfma_f32_32x32x16_bf16 v[240:255], v[60:63], v[232:235], v[240:255]
	v_max_i32_e32 v2, 0, v2
	v_fmac_f32_e32 v126, v238, v2
	v_max_i32_e32 v3, 0, v3
	v_fmac_f32_e32 v127, v238, v3
	v_max_i32_e32 v4, 0, v4
	v_fmac_f32_e32 v124, v238, v4
	v_max_i32_e32 v5, 0, v5
	v_fmac_f32_e32 v125, v238, v5
	v_max_i32_e32 v6, 0, v6
	v_fmac_f32_e32 v122, v238, v6
	v_max_i32_e32 v7, 0, v7
	v_fmac_f32_e32 v123, v238, v7
	v_max_i32_e32 v8, 0, v8
	v_fmac_f32_e32 v120, v238, v8
	v_max_i32_e32 v9, 0, v9
	v_fmac_f32_e32 v121, v238, v9
	v_max_i32_e32 v10, 0, v10
	v_fmac_f32_e32 v118, v238, v10
	v_max_i32_e32 v11, 0, v11
	v_fmac_f32_e32 v119, v238, v11
	v_max_i32_e32 v12, 0, v12
	v_fmac_f32_e32 v116, v238, v12
	v_max_i32_e32 v13, 0, v13
	v_fmac_f32_e32 v117, v238, v13
	v_max_i32_e32 v14, 0, v14
	v_fmac_f32_e32 v114, v238, v14
	v_max_i32_e32 v15, 0, v15
	v_fmac_f32_e32 v115, v238, v15
	v_max_i32_e32 v16, 0, v16
	v_fmac_f32_e32 v112, v238, v16
	v_max_i32_e32 v17, 0, v17
	v_fmac_f32_e32 v113, v238, v17
	v_mfma_f32_32x32x16_bf16 v[2:17], v[56:59], v[228:231], 0
	v_mfma_f32_32x32x16_bf16 v[2:17], v[52:55], v[232:235], v[2:17]
	ds_read_b128 v[228:231], v147 offset:128
	ds_read_b128 v[232:235], v147 offset:160
	v_max_i32_e32 v18, 0, v18
	v_fmac_f32_e32 v110, v238, v18
	v_max_i32_e32 v19, 0, v19
	v_fmac_f32_e32 v111, v238, v19
	v_max_i32_e32 v20, 0, v20
	v_fmac_f32_e32 v108, v238, v20
	v_max_i32_e32 v21, 0, v21
	v_fmac_f32_e32 v109, v238, v21
	v_max_i32_e32 v22, 0, v22
	v_fmac_f32_e32 v106, v238, v22
	v_max_i32_e32 v23, 0, v23
	v_fmac_f32_e32 v107, v238, v23
	v_max_i32_e32 v24, 0, v24
	v_fmac_f32_e32 v104, v238, v24
	v_max_i32_e32 v25, 0, v25
	v_fmac_f32_e32 v105, v238, v25
	v_max_i32_e32 v26, 0, v26
	v_fmac_f32_e32 v102, v238, v26
	v_max_i32_e32 v27, 0, v27
	v_fmac_f32_e32 v103, v238, v27
	v_max_i32_e32 v28, 0, v28
	v_fmac_f32_e32 v100, v238, v28
	v_max_i32_e32 v29, 0, v29
	v_fmac_f32_e32 v101, v238, v29
	v_max_i32_e32 v30, 0, v30
	v_fmac_f32_e32 v98, v238, v30
	v_max_i32_e32 v31, 0, v31
	v_fmac_f32_e32 v99, v238, v31
	v_max_i32_e32 v32, 0, v32
	v_fmac_f32_e32 v96, v238, v32
	v_max_i32_e32 v33, 0, v33
	v_fmac_f32_e32 v97, v238, v33
	ds_read_b32 v238, v153 offset:256
	s_waitcnt lgkmcnt(1)
	v_mfma_f32_32x32x16_bf16 v[18:33], v[64:67], v[228:231], 0
	v_mfma_f32_32x32x16_bf16 v[18:33], v[60:63], v[232:235], v[18:33]
	v_max_i32_e32 v240, 0, v240
	v_fmac_f32_e32 v126, v239, v240
	v_max_i32_e32 v241, 0, v241
	v_fmac_f32_e32 v127, v239, v241
	v_max_i32_e32 v242, 0, v242
	v_fmac_f32_e32 v124, v239, v242
	v_max_i32_e32 v243, 0, v243
	v_fmac_f32_e32 v125, v239, v243
	v_max_i32_e32 v244, 0, v244
	v_fmac_f32_e32 v122, v239, v244
	v_max_i32_e32 v245, 0, v245
	v_fmac_f32_e32 v123, v239, v245
	v_max_i32_e32 v246, 0, v246
	v_fmac_f32_e32 v120, v239, v246
	v_max_i32_e32 v247, 0, v247
	v_fmac_f32_e32 v121, v239, v247
	v_max_i32_e32 v248, 0, v248
	v_fmac_f32_e32 v118, v239, v248
	v_max_i32_e32 v249, 0, v249
	v_fmac_f32_e32 v119, v239, v249
	v_max_i32_e32 v250, 0, v250
	v_fmac_f32_e32 v116, v239, v250
	v_max_i32_e32 v251, 0, v251
	v_fmac_f32_e32 v117, v239, v251
	v_max_i32_e32 v252, 0, v252
	v_fmac_f32_e32 v114, v239, v252
	v_max_i32_e32 v253, 0, v253
	v_fmac_f32_e32 v115, v239, v253
	v_max_i32_e32 v254, 0, v254
	v_fmac_f32_e32 v112, v239, v254
	v_max_i32_e32 v255, 0, v255
	v_fmac_f32_e32 v113, v239, v255
	v_mfma_f32_32x32x16_bf16 v[240:255], v[56:59], v[228:231], 0
	v_mfma_f32_32x32x16_bf16 v[240:255], v[52:55], v[232:235], v[240:255]
	ds_read_b128 v[228:231], v147 offset:192
	ds_read_b128 v[232:235], v147 offset:224
	v_max_i32_e32 v2, 0, v2
	v_fmac_f32_e32 v110, v239, v2
	v_max_i32_e32 v3, 0, v3
	v_fmac_f32_e32 v111, v239, v3
	v_max_i32_e32 v4, 0, v4
	v_fmac_f32_e32 v108, v239, v4
	v_max_i32_e32 v5, 0, v5
	v_fmac_f32_e32 v109, v239, v5
	v_max_i32_e32 v6, 0, v6
	v_fmac_f32_e32 v106, v239, v6
	v_max_i32_e32 v7, 0, v7
	v_fmac_f32_e32 v107, v239, v7
	v_max_i32_e32 v8, 0, v8
	v_fmac_f32_e32 v104, v239, v8
	v_max_i32_e32 v9, 0, v9
	v_fmac_f32_e32 v105, v239, v9
	v_max_i32_e32 v10, 0, v10
	v_fmac_f32_e32 v102, v239, v10
	v_max_i32_e32 v11, 0, v11
	v_fmac_f32_e32 v103, v239, v11
	v_max_i32_e32 v12, 0, v12
	v_fmac_f32_e32 v100, v239, v12
	v_max_i32_e32 v13, 0, v13
	v_fmac_f32_e32 v101, v239, v13
	v_max_i32_e32 v14, 0, v14
	v_fmac_f32_e32 v98, v239, v14
	v_max_i32_e32 v15, 0, v15
	v_fmac_f32_e32 v99, v239, v15
	v_max_i32_e32 v16, 0, v16
	v_fmac_f32_e32 v96, v239, v16
	v_max_i32_e32 v17, 0, v17
	v_fmac_f32_e32 v97, v239, v17
	ds_read_b32 v239, v153 offset:384
	s_waitcnt lgkmcnt(1)
; #define MFMA32(a, b, c) __builtin_amdgcn_mfma_f32_32x32x16_bf16((a), (b), (c), 0, 0, 0)
; DI f32x16 zero16() { f32x16 z; for (int i = 0; i < 16; i++) z[i] = 0.f; return z; }
; DI void dsa_item(const Params& P, int layer, int b, int qt, char* mb, char* smem) {
;     ...
; #pragma unroll 2
;       for (int hd = 0; hd < 8; hd++) {
;         const bf16x8 q0f = *(const bf16x8*)(sQi + r * 528 + hd * 64 + hh * 16);
;         const bf16x8 q1f = *(const bf16x8*)(sQi + r * 528 + hd * 64 + 32 + hh * 16);
;         const float w = sWi[hd * 32 + r];
;         f32x16 sa = MFMA32(kA0, q0f, zero16());
;         f32x16 sb = MFMA32(kB0, q0f, zero16());
;         sa = MFMA32(kA1, q1f, sa);
;         sb = MFMA32(kB1, q1f, sb);
; #pragma unroll
;         for (int i = 0; i < 16; i++) {
;           scA[i] += __int_as_float(max(__float_as_int(sa[i]), 0)) * w;
;           scB[i] += __int_as_float(max(__float_as_int(sb[i]), 0)) * w;
;         }
;       }
	v_mfma_f32_32x32x16_bf16 v[2:17], v[64:67], v[228:231], 0
	v_mfma_f32_32x32x16_bf16 v[2:17], v[60:63], v[232:235], v[2:17]
	v_max_i32_e32 v18, 0, v18
	v_fmac_f32_e32 v126, v238, v18
	v_max_i32_e32 v19, 0, v19
	v_fmac_f32_e32 v127, v238, v19
	v_max_i32_e32 v20, 0, v20
	v_fmac_f32_e32 v124, v238, v20
	v_max_i32_e32 v21, 0, v21
	v_fmac_f32_e32 v125, v238, v21
	v_max_i32_e32 v22, 0, v22
	v_fmac_f32_e32 v122, v238, v22
	v_max_i32_e32 v23, 0, v23
	v_fmac_f32_e32 v123, v238, v23
	v_max_i32_e32 v24, 0, v24
	v_fmac_f32_e32 v120, v238, v24
	v_max_i32_e32 v25, 0, v25
	v_fmac_f32_e32 v121, v238, v25
	v_max_i32_e32 v26, 0, v26
	v_fmac_f32_e32 v118, v238, v26
	v_max_i32_e32 v27, 0, v27
	v_fmac_f32_e32 v119, v238, v27
	v_max_i32_e32 v28, 0, v28
	v_fmac_f32_e32 v116, v238, v28
	v_max_i32_e32 v29, 0, v29
	v_fmac_f32_e32 v117, v238, v29
	v_max_i32_e32 v30, 0, v30
	v_fmac_f32_e32 v114, v238, v30
	v_max_i32_e32 v31, 0, v31
	v_fmac_f32_e32 v115, v238, v31
	v_max_i32_e32 v32, 0, v32
	v_fmac_f32_e32 v112, v238, v32
	v_max_i32_e32 v33, 0, v33
	v_fmac_f32_e32 v113, v238, v33
	v_mfma_f32_32x32x16_bf16 v[18:33], v[56:59], v[228:231], 0
	v_mfma_f32_32x32x16_bf16 v[18:33], v[52:55], v[232:235], v[18:33]
	ds_read_b128 v[228:231], v147 offset:256
	ds_read_b128 v[232:235], v147 offset:288
	v_max_i32_e32 v240, 0, v240
	v_fmac_f32_e32 v110, v238, v240
	v_max_i32_e32 v241, 0, v241
	v_fmac_f32_e32 v111, v238, v241
	v_max_i32_e32 v242, 0, v242
	v_fmac_f32_e32 v108, v238, v242
	v_max_i32_e32 v243, 0, v243
	v_fmac_f32_e32 v109, v238, v243
	v_max_i32_e32 v244, 0, v244
	v_fmac_f32_e32 v106, v238, v244
	v_max_i32_e32 v245, 0, v245
	v_fmac_f32_e32 v107, v238, v245
	v_max_i32_e32 v246, 0, v246
	v_fmac_f32_e32 v104, v238, v246
	v_max_i32_e32 v247, 0, v247
	v_fmac_f32_e32 v105, v238, v247
	v_max_i32_e32 v248, 0, v248
	v_fmac_f32_e32 v102, v238, v248
	v_max_i32_e32 v249, 0, v249
	v_fmac_f32_e32 v103, v238, v249
	v_max_i32_e32 v250, 0, v250
	v_fmac_f32_e32 v100, v238, v250
	v_max_i32_e32 v251, 0, v251
	v_fmac_f32_e32 v101, v238, v251
	v_max_i32_e32 v252, 0, v252
	v_fmac_f32_e32 v98, v238, v252
	v_max_i32_e32 v253, 0, v253
	v_fmac_f32_e32 v99, v238, v253
	v_max_i32_e32 v254, 0, v254
	v_fmac_f32_e32 v96, v238, v254
	v_max_i32_e32 v255, 0, v255
	v_fmac_f32_e32 v97, v238, v255
	ds_read_b32 v238, v153 offset:512
	s_waitcnt lgkmcnt(1)
	v_mfma_f32_32x32x16_bf16 v[240:255], v[64:67], v[228:231], 0
	v_mfma_f32_32x32x16_bf16 v[240:255], v[60:63], v[232:235], v[240:255]
	v_max_i32_e32 v2, 0, v2
	v_fmac_f32_e32 v126, v239, v2
	v_max_i32_e32 v3, 0, v3
	v_fmac_f32_e32 v127, v239, v3
	v_max_i32_e32 v4, 0, v4
	v_fmac_f32_e32 v124, v239, v4
	v_max_i32_e32 v5, 0, v5
	v_fmac_f32_e32 v125, v239, v5
	v_max_i32_e32 v6, 0, v6
	v_fmac_f32_e32 v122, v239, v6
	v_max_i32_e32 v7, 0, v7
	v_fmac_f32_e32 v123, v239, v7
	v_max_i32_e32 v8, 0, v8
	v_fmac_f32_e32 v120, v239, v8
	v_max_i32_e32 v9, 0, v9
	v_fmac_f32_e32 v121, v239, v9
	v_max_i32_e32 v10, 0, v10
	v_fmac_f32_e32 v118, v239, v10
	v_max_i32_e32 v11, 0, v11
	v_fmac_f32_e32 v119, v239, v11
	v_max_i32_e32 v12, 0, v12
	v_fmac_f32_e32 v116, v239, v12
	v_max_i32_e32 v13, 0, v13
	v_fmac_f32_e32 v117, v239, v13
	v_max_i32_e32 v14, 0, v14
	v_fmac_f32_e32 v114, v239, v14
	v_max_i32_e32 v15, 0, v15
	v_fmac_f32_e32 v115, v239, v15
	v_max_i32_e32 v16, 0, v16
	v_fmac_f32_e32 v112, v239, v16
	v_max_i32_e32 v17, 0, v17
	v_fmac_f32_e32 v113, v239, v17
	v_mfma_f32_32x32x16_bf16 v[2:17], v[56:59], v[228:231], 0
	v_mfma_f32_32x32x16_bf16 v[2:17], v[52:55], v[232:235], v[2:17]
	ds_read_b128 v[228:231], v147 offset:320
	ds_read_b128 v[232:235], v147 offset:352
	v_max_i32_e32 v18, 0, v18
	v_fmac_f32_e32 v110, v239, v18
	v_max_i32_e32 v19, 0, v19
	v_fmac_f32_e32 v111, v239, v19
	v_max_i32_e32 v20, 0, v20
	v_fmac_f32_e32 v108, v239, v20
	v_max_i32_e32 v21, 0, v21
	v_fmac_f32_e32 v109, v239, v21
	v_max_i32_e32 v22, 0, v22
	v_fmac_f32_e32 v106, v239, v22
	v_max_i32_e32 v23, 0, v23
	v_fmac_f32_e32 v107, v239, v23
	v_max_i32_e32 v24, 0, v24
	v_fmac_f32_e32 v104, v239, v24
	v_max_i32_e32 v25, 0, v25
	v_fmac_f32_e32 v105, v239, v25
	v_max_i32_e32 v26, 0, v26
	v_fmac_f32_e32 v102, v239, v26
	v_max_i32_e32 v27, 0, v27
	v_fmac_f32_e32 v103, v239, v27
	v_max_i32_e32 v28, 0, v28
	v_fmac_f32_e32 v100, v239, v28
	v_max_i32_e32 v29, 0, v29
	v_fmac_f32_e32 v101, v239, v29
	v_max_i32_e32 v30, 0, v30
	v_fmac_f32_e32 v98, v239, v30
	v_max_i32_e32 v31, 0, v31
	v_fmac_f32_e32 v99, v239, v31
	v_max_i32_e32 v32, 0, v32
	v_fmac_f32_e32 v96, v239, v32
	v_max_i32_e32 v33, 0, v33
	v_fmac_f32_e32 v97, v239, v33
	ds_read_b32 v239, v153 offset:640
	s_waitcnt lgkmcnt(1)
; #define MFMA32(a, b, c) __builtin_amdgcn_mfma_f32_32x32x16_bf16((a), (b), (c), 0, 0, 0)
; DI f32x16 zero16() { f32x16 z; for (int i = 0; i < 16; i++) z[i] = 0.f; return z; }
; DI void dsa_item(const Params& P, int layer, int b, int qt, char* mb, char* smem) {
;     ...
; #pragma unroll 2
;       for (int hd = 0; hd < 8; hd++) {
;         const bf16x8 q0f = *(const bf16x8*)(sQi + r * 528 + hd * 64 + hh * 16);
;         const bf16x8 q1f = *(const bf16x8*)(sQi + r * 528 + hd * 64 + 32 + hh * 16);
;         const float w = sWi[hd * 32 + r];
;         f32x16 sa = MFMA32(kA0, q0f, zero16());
;         f32x16 sb = MFMA32(kB0, q0f, zero16());
;         sa = MFMA32(kA1, q1f, sa);
;         sb = MFMA32(kB1, q1f, sb);
; #pragma unroll
;         for (int i = 0; i < 16; i++) {
;           scA[i] += __int_as_float(max(__float_as_int(sa[i]), 0)) * w;
;           scB[i] += __int_as_float(max(__float_as_int(sb[i]), 0)) * w;
;         }
;       }
	v_mfma_f32_32x32x16_bf16 v[18:33], v[64:67], v[228:231], 0
	v_mfma_f32_32x32x16_bf16 v[18:33], v[60:63], v[232:235], v[18:33]
	v_max_i32_e32 v240, 0, v240
	v_fmac_f32_e32 v126, v238, v240
	v_max_i32_e32 v241, 0, v241
	v_fmac_f32_e32 v127, v238, v241
	v_max_i32_e32 v242, 0, v242
	v_fmac_f32_e32 v124, v238, v242
	v_max_i32_e32 v243, 0, v243
	v_fmac_f32_e32 v125, v238, v243
	v_max_i32_e32 v244, 0, v244
	v_fmac_f32_e32 v122, v238, v244
	v_max_i32_e32 v245, 0, v245
	v_fmac_f32_e32 v123, v238, v245
	v_max_i32_e32 v246, 0, v246
	v_fmac_f32_e32 v120, v238, v246
	v_max_i32_e32 v247, 0, v247
	v_fmac_f32_e32 v121, v238, v247
	v_max_i32_e32 v248, 0, v248
	v_fmac_f32_e32 v118, v238, v248
	v_max_i32_e32 v249, 0, v249
	v_fmac_f32_e32 v119, v238, v249
	v_max_i32_e32 v250, 0, v250
	v_fmac_f32_e32 v116, v238, v250
	v_max_i32_e32 v251, 0, v251
	v_fmac_f32_e32 v117, v238, v251
	v_max_i32_e32 v252, 0, v252
	v_fmac_f32_e32 v114, v238, v252
	v_max_i32_e32 v253, 0, v253
	v_fmac_f32_e32 v115, v238, v253
	v_max_i32_e32 v254, 0, v254
	v_fmac_f32_e32 v112, v238, v254
	v_max_i32_e32 v255, 0, v255
	v_fmac_f32_e32 v113, v238, v255
	v_mfma_f32_32x32x16_bf16 v[240:255], v[56:59], v[228:231], 0
	v_mfma_f32_32x32x16_bf16 v[240:255], v[52:55], v[232:235], v[240:255]
	ds_read_b128 v[228:231], v147 offset:384
	ds_read_b128 v[232:235], v147 offset:416
	v_max_i32_e32 v2, 0, v2
	v_fmac_f32_e32 v110, v238, v2
	v_max_i32_e32 v3, 0, v3
	v_fmac_f32_e32 v111, v238, v3
	v_max_i32_e32 v4, 0, v4
	v_fmac_f32_e32 v108, v238, v4
	v_max_i32_e32 v5, 0, v5
	v_fmac_f32_e32 v109, v238, v5
	v_max_i32_e32 v6, 0, v6
	v_fmac_f32_e32 v106, v238, v6
	v_max_i32_e32 v7, 0, v7
	v_fmac_f32_e32 v107, v238, v7
	v_max_i32_e32 v8, 0, v8
	v_fmac_f32_e32 v104, v238, v8
	v_max_i32_e32 v9, 0, v9
	v_fmac_f32_e32 v105, v238, v9
	v_max_i32_e32 v10, 0, v10
	v_fmac_f32_e32 v102, v238, v10
	v_max_i32_e32 v11, 0, v11
	v_fmac_f32_e32 v103, v238, v11
	v_max_i32_e32 v12, 0, v12
	v_fmac_f32_e32 v100, v238, v12
	v_max_i32_e32 v13, 0, v13
	v_fmac_f32_e32 v101, v238, v13
	v_max_i32_e32 v14, 0, v14
	v_fmac_f32_e32 v98, v238, v14
	v_max_i32_e32 v15, 0, v15
	v_fmac_f32_e32 v99, v238, v15
	v_max_i32_e32 v16, 0, v16
	v_fmac_f32_e32 v96, v238, v16
	v_max_i32_e32 v17, 0, v17
	v_fmac_f32_e32 v97, v238, v17
	ds_read_b32 v238, v153 offset:768
	s_waitcnt lgkmcnt(1)
	v_mfma_f32_32x32x16_bf16 v[2:17], v[64:67], v[228:231], 0
	v_mfma_f32_32x32x16_bf16 v[2:17], v[60:63], v[232:235], v[2:17]
	v_max_i32_e32 v18, 0, v18
	v_fmac_f32_e32 v126, v239, v18
	v_max_i32_e32 v19, 0, v19
	v_fmac_f32_e32 v127, v239, v19
	v_max_i32_e32 v20, 0, v20
	v_fmac_f32_e32 v124, v239, v20
	v_max_i32_e32 v21, 0, v21
	v_fmac_f32_e32 v125, v239, v21
	v_max_i32_e32 v22, 0, v22
	v_fmac_f32_e32 v122, v239, v22
	v_max_i32_e32 v23, 0, v23
	v_fmac_f32_e32 v123, v239, v23
	v_max_i32_e32 v24, 0, v24
	v_fmac_f32_e32 v120, v239, v24
	v_max_i32_e32 v25, 0, v25
	v_fmac_f32_e32 v121, v239, v25
	v_max_i32_e32 v26, 0, v26
	v_fmac_f32_e32 v118, v239, v26
	v_max_i32_e32 v27, 0, v27
	v_fmac_f32_e32 v119, v239, v27
	v_max_i32_e32 v28, 0, v28
	v_fmac_f32_e32 v116, v239, v28
	v_max_i32_e32 v29, 0, v29
	v_fmac_f32_e32 v117, v239, v29
	v_max_i32_e32 v30, 0, v30
	v_fmac_f32_e32 v114, v239, v30
	v_max_i32_e32 v31, 0, v31
	v_fmac_f32_e32 v115, v239, v31
	v_max_i32_e32 v32, 0, v32
	v_fmac_f32_e32 v112, v239, v32
	v_max_i32_e32 v33, 0, v33
	v_fmac_f32_e32 v113, v239, v33
	v_mfma_f32_32x32x16_bf16 v[18:33], v[56:59], v[228:231], 0
	v_mfma_f32_32x32x16_bf16 v[18:33], v[52:55], v[232:235], v[18:33]
	ds_read_b128 v[228:231], v147 offset:448
	ds_read_b128 v[232:235], v147 offset:480
	v_max_i32_e32 v240, 0, v240
	v_fmac_f32_e32 v110, v239, v240
	v_max_i32_e32 v241, 0, v241
	v_fmac_f32_e32 v111, v239, v241
	v_max_i32_e32 v242, 0, v242
	v_fmac_f32_e32 v108, v239, v242
	v_max_i32_e32 v243, 0, v243
	v_fmac_f32_e32 v109, v239, v243
	v_max_i32_e32 v244, 0, v244
	v_fmac_f32_e32 v106, v239, v244
	v_max_i32_e32 v245, 0, v245
	v_fmac_f32_e32 v107, v239, v245
	v_max_i32_e32 v246, 0, v246
	v_fmac_f32_e32 v104, v239, v246
	v_max_i32_e32 v247, 0, v247
	v_fmac_f32_e32 v105, v239, v247
	v_max_i32_e32 v248, 0, v248
	v_fmac_f32_e32 v102, v239, v248
	v_max_i32_e32 v249, 0, v249
	v_fmac_f32_e32 v103, v239, v249
	v_max_i32_e32 v250, 0, v250
	v_fmac_f32_e32 v100, v239, v250
	v_max_i32_e32 v251, 0, v251
	v_fmac_f32_e32 v101, v239, v251
	v_max_i32_e32 v252, 0, v252
	v_fmac_f32_e32 v98, v239, v252
	v_max_i32_e32 v253, 0, v253
	v_fmac_f32_e32 v99, v239, v253
	v_max_i32_e32 v254, 0, v254
	v_fmac_f32_e32 v96, v239, v254
	v_max_i32_e32 v255, 0, v255
	v_fmac_f32_e32 v97, v239, v255
	ds_read_b32 v239, v153 offset:896
	s_waitcnt lgkmcnt(1)
; #define MFMA32(a, b, c) __builtin_amdgcn_mfma_f32_32x32x16_bf16((a), (b), (c), 0, 0, 0)
; DI f32x16 zero16() { f32x16 z; for (int i = 0; i < 16; i++) z[i] = 0.f; return z; }
; DI void dsa_item(const Params& P, int layer, int b, int qt, char* mb, char* smem) {
;     ...
; #pragma unroll 2
;       for (int hd = 0; hd < 8; hd++) {
;         const bf16x8 q0f = *(const bf16x8*)(sQi + r * 528 + hd * 64 + hh * 16);
;         const bf16x8 q1f = *(const bf16x8*)(sQi + r * 528 + hd * 64 + 32 + hh * 16);
;         const float w = sWi[hd * 32 + r];
;         f32x16 sa = MFMA32(kA0, q0f, zero16());
;         f32x16 sb = MFMA32(kB0, q0f, zero16());
;         sa = MFMA32(kA1, q1f, sa);
;         sb = MFMA32(kB1, q1f, sb);
; #pragma unroll
;         for (int i = 0; i < 16; i++) {
;           scA[i] += __int_as_float(max(__float_as_int(sa[i]), 0)) * w;
;           scB[i] += __int_as_float(max(__float_as_int(sb[i]), 0)) * w;
;         }
;       }
;       elems(scA, kt, (kt == qt) ? qp : 0x7fffffff);
;       if (kt + 4 < nk32) elems(scB, kt + 4, (kt + 4 == qt) ? qp : 0x7fffffff);
	v_mfma_f32_32x32x16_bf16 v[240:255], v[64:67], v[228:231], 0
	v_mfma_f32_32x32x16_bf16 v[240:255], v[60:63], v[232:235], v[240:255]
	v_max_i32_e32 v2, 0, v2
	v_fmac_f32_e32 v126, v238, v2
	v_max_i32_e32 v3, 0, v3
	v_fmac_f32_e32 v127, v238, v3
	v_max_i32_e32 v4, 0, v4
	v_fmac_f32_e32 v124, v238, v4
	v_max_i32_e32 v5, 0, v5
	v_fmac_f32_e32 v125, v238, v5
	v_max_i32_e32 v6, 0, v6
	v_fmac_f32_e32 v122, v238, v6
	v_max_i32_e32 v7, 0, v7
	v_fmac_f32_e32 v123, v238, v7
	v_max_i32_e32 v8, 0, v8
	v_fmac_f32_e32 v120, v238, v8
	v_max_i32_e32 v9, 0, v9
	v_fmac_f32_e32 v121, v238, v9
	v_max_i32_e32 v10, 0, v10
	v_fmac_f32_e32 v118, v238, v10
	v_max_i32_e32 v11, 0, v11
	v_fmac_f32_e32 v119, v238, v11
	v_max_i32_e32 v12, 0, v12
	v_fmac_f32_e32 v116, v238, v12
	v_max_i32_e32 v13, 0, v13
	v_fmac_f32_e32 v117, v238, v13
	v_max_i32_e32 v14, 0, v14
	v_fmac_f32_e32 v114, v238, v14
	v_max_i32_e32 v15, 0, v15
	v_fmac_f32_e32 v115, v238, v15
	v_max_i32_e32 v16, 0, v16
	v_fmac_f32_e32 v112, v238, v16
	v_max_i32_e32 v17, 0, v17
	v_fmac_f32_e32 v113, v238, v17
	v_mfma_f32_32x32x16_bf16 v[2:17], v[56:59], v[228:231], 0
	v_mfma_f32_32x32x16_bf16 v[2:17], v[52:55], v[232:235], v[2:17]
	v_max_i32_e32 v18, 0, v18
	v_fmac_f32_e32 v110, v238, v18
	v_max_i32_e32 v19, 0, v19
	v_fmac_f32_e32 v111, v238, v19
	v_max_i32_e32 v20, 0, v20
	v_fmac_f32_e32 v108, v238, v20
	v_max_i32_e32 v21, 0, v21
	v_fmac_f32_e32 v109, v238, v21
	v_max_i32_e32 v22, 0, v22
	v_fmac_f32_e32 v106, v238, v22
	v_max_i32_e32 v23, 0, v23
	v_fmac_f32_e32 v107, v238, v23
	v_max_i32_e32 v24, 0, v24
	v_fmac_f32_e32 v104, v238, v24
	v_max_i32_e32 v25, 0, v25
	v_fmac_f32_e32 v105, v238, v25
	v_max_i32_e32 v26, 0, v26
	v_fmac_f32_e32 v102, v238, v26
	v_max_i32_e32 v27, 0, v27
	v_fmac_f32_e32 v103, v238, v27
	v_max_i32_e32 v28, 0, v28
	v_fmac_f32_e32 v100, v238, v28
	v_max_i32_e32 v29, 0, v29
	v_fmac_f32_e32 v101, v238, v29
	v_max_i32_e32 v30, 0, v30
	v_fmac_f32_e32 v98, v238, v30
	v_max_i32_e32 v31, 0, v31
	v_fmac_f32_e32 v99, v238, v31
	v_max_i32_e32 v32, 0, v32
	v_fmac_f32_e32 v96, v238, v32
	v_max_i32_e32 v33, 0, v33
	v_fmac_f32_e32 v97, v238, v33
	s_waitcnt lgkmcnt(0)
	v_max_i32_e32 v240, 0, v240
	v_fmac_f32_e32 v126, v239, v240
	v_max_i32_e32 v241, 0, v241
	v_fmac_f32_e32 v127, v239, v241
	v_max_i32_e32 v242, 0, v242
	v_fmac_f32_e32 v124, v239, v242
	v_max_i32_e32 v243, 0, v243
	v_fmac_f32_e32 v125, v239, v243
	v_max_i32_e32 v244, 0, v244
	v_fmac_f32_e32 v122, v239, v244
	v_max_i32_e32 v245, 0, v245
	v_fmac_f32_e32 v123, v239, v245
	v_max_i32_e32 v246, 0, v246
	v_fmac_f32_e32 v120, v239, v246
	v_max_i32_e32 v247, 0, v247
	v_fmac_f32_e32 v121, v239, v247
	v_max_i32_e32 v248, 0, v248
	v_fmac_f32_e32 v118, v239, v248
	v_max_i32_e32 v249, 0, v249
	v_fmac_f32_e32 v119, v239, v249
	v_max_i32_e32 v250, 0, v250
	v_fmac_f32_e32 v116, v239, v250
	v_max_i32_e32 v251, 0, v251
	v_fmac_f32_e32 v117, v239, v251
	v_max_i32_e32 v252, 0, v252
	v_fmac_f32_e32 v114, v239, v252
	v_max_i32_e32 v253, 0, v253
	v_fmac_f32_e32 v115, v239, v253
	v_max_i32_e32 v254, 0, v254
	v_fmac_f32_e32 v112, v239, v254
	v_max_i32_e32 v255, 0, v255
	v_fmac_f32_e32 v113, v239, v255
	v_max_i32_e32 v2, 0, v2
	v_fmac_f32_e32 v110, v239, v2
	v_max_i32_e32 v3, 0, v3
	v_fmac_f32_e32 v111, v239, v3
	v_max_i32_e32 v4, 0, v4
	v_fmac_f32_e32 v108, v239, v4
	v_max_i32_e32 v5, 0, v5
	v_fmac_f32_e32 v109, v239, v5
	v_max_i32_e32 v6, 0, v6
	v_fmac_f32_e32 v106, v239, v6
	v_max_i32_e32 v7, 0, v7
	v_fmac_f32_e32 v107, v239, v7
	v_max_i32_e32 v8, 0, v8
	v_fmac_f32_e32 v104, v239, v8
	v_max_i32_e32 v9, 0, v9
	v_fmac_f32_e32 v105, v239, v9
	v_max_i32_e32 v10, 0, v10
	v_fmac_f32_e32 v102, v239, v10
	v_max_i32_e32 v11, 0, v11
	v_fmac_f32_e32 v103, v239, v11
	v_max_i32_e32 v12, 0, v12
	v_fmac_f32_e32 v100, v239, v12
	v_max_i32_e32 v13, 0, v13
	v_fmac_f32_e32 v101, v239, v13
	v_max_i32_e32 v14, 0, v14
	v_fmac_f32_e32 v98, v239, v14
	v_max_i32_e32 v15, 0, v15
	v_fmac_f32_e32 v99, v239, v15
	v_max_i32_e32 v16, 0, v16
	v_fmac_f32_e32 v96, v239, v16
	v_max_i32_e32 v17, 0, v17
	v_fmac_f32_e32 v97, v239, v17
	s_movk_i32 s0, 0x200
	v_cmp_eq_u32_e32 vcc, s57, v151
	v_lshlrev_b32_e32 v31, 5, v151
	s_nop 0
	v_cndmask_b32_e32 v30, v201, v136, vcc
	s_and_b64 vcc, exec, s[92:93]
	s_cbranch_vccz .LBB0_3290
	s_andn2_b64 vcc, exec, s[88:89]
	s_mov_b64 s[0:1], -1
	s_cbranch_vccnz .LBB0_3282
; DI int crow(int i, int hh) { return (i & 3) + 8 * (i >> 2) + 4 * hh; }
; DI unsigned sortkey(float f) { const unsigned u = __float_as_uint(f + 0.f); return u ^ (((unsigned)((int)u >> 31)) | 0x80000000u); }
; DI void dsa_item(const Params& P, int layer, int b, int qt, char* mb, char* smem) {
;     ...
;       } else if (pass < 4) {
;         const int sh = 24 - 8 * pass;
; #pragma unroll
;         for (int i = 0; i < 16; i++) {
;           const int kp = kt * 32 + crow(i, hh);
;           const unsigned key = sortkey(sc[i]);
;           if ((key >> (sh + 8)) == pref && kp <= lim) atomicAdd(&hist[r * 257 + ((key >> sh) & 255u)], 1u);
;         }
	v_add_f32_e32 v2, 0, v126
	v_ashrrev_i32_e32 v3, 31, v2
	v_bitop3_b32 v3, v3, v2, s96 bitop3:0x36
	v_lshrrev_b32_e32 v2, s33, v3
	v_cmp_eq_u32_e32 vcc, v2, v94
	v_or_b32_e32 v2, v31, v133
	v_cmp_le_i32_e64 s[0:1], v2, v30
	s_and_b64 s[18:19], vcc, s[0:1]
	s_and_saveexec_b64 s[0:1], s[18:19]
	v_bfe_u32 v3, v3, s55, 8
	v_lshl_add_u32 v3, v3, 2, v144
	ds_add_u32 v3, v192
	s_or_b64 exec, exec, s[0:1]
	v_add_f32_e32 v3, 0, v127
	v_ashrrev_i32_e32 v4, 31, v3
	v_bitop3_b32 v3, v4, v3, s96 bitop3:0x36
	v_lshrrev_b32_e32 v4, s33, v3
	v_cmp_eq_u32_e32 vcc, v4, v94
	v_cmp_lt_i32_e64 s[0:1], v2, v30
	s_and_b64 s[18:19], vcc, s[0:1]
	s_and_saveexec_b64 s[0:1], s[18:19]
	v_bfe_u32 v2, v3, s55, 8
	v_lshl_add_u32 v2, v2, 2, v144
	ds_add_u32 v2, v192
	s_or_b64 exec, exec, s[0:1]
	v_add_f32_e32 v2, 0, v124
	v_ashrrev_i32_e32 v3, 31, v2
	v_bitop3_b32 v2, v3, v2, s96 bitop3:0x36
	v_lshrrev_b32_e32 v3, s33, v2
	v_cmp_eq_u32_e32 vcc, v3, v94
	v_or_b32_e32 v3, v31, v74
	v_cmp_le_i32_e64 s[0:1], v3, v30
	s_and_b64 s[18:19], vcc, s[0:1]
	s_and_saveexec_b64 s[0:1], s[18:19]
	v_bfe_u32 v2, v2, s55, 8
	v_lshl_add_u32 v2, v2, 2, v144
	ds_add_u32 v2, v192
	s_or_b64 exec, exec, s[0:1]
	v_add_f32_e32 v2, 0, v125
	v_ashrrev_i32_e32 v3, 31, v2
	v_bitop3_b32 v2, v3, v2, s96 bitop3:0x36
	v_lshrrev_b32_e32 v3, s33, v2
	v_cmp_eq_u32_e32 vcc, v3, v94
	v_or_b32_e32 v3, v31, v1
	v_cmp_le_i32_e64 s[0:1], v3, v30
	s_and_b64 s[18:19], vcc, s[0:1]
	s_and_saveexec_b64 s[0:1], s[18:19]
	v_bfe_u32 v2, v2, s55, 8
	v_lshl_add_u32 v2, v2, 2, v144
	ds_add_u32 v2, v192
	s_or_b64 exec, exec, s[0:1]
	v_add_f32_e32 v2, 0, v122
	v_ashrrev_i32_e32 v3, 31, v2
	v_bitop3_b32 v2, v3, v2, s96 bitop3:0x36
	v_lshrrev_b32_e32 v3, s33, v2
	v_cmp_eq_u32_e32 vcc, v3, v94
	v_or_b32_e32 v3, v31, v76
	v_cmp_le_i32_e64 s[0:1], v3, v30
	s_and_b64 s[18:19], vcc, s[0:1]
	s_and_saveexec_b64 s[0:1], s[18:19]
	v_bfe_u32 v2, v2, s55, 8
	v_lshl_add_u32 v2, v2, 2, v144
	ds_add_u32 v2, v192
	s_or_b64 exec, exec, s[0:1]
	v_add_f32_e32 v2, 0, v123
	v_ashrrev_i32_e32 v3, 31, v2
	v_bitop3_b32 v2, v3, v2, s96 bitop3:0x36
	v_lshrrev_b32_e32 v3, s33, v2
	v_cmp_eq_u32_e32 vcc, v3, v94
	v_or_b32_e32 v3, v31, v69
	v_cmp_le_i32_e64 s[0:1], v3, v30
	s_and_b64 s[18:19], vcc, s[0:1]
	s_and_saveexec_b64 s[0:1], s[18:19]
	v_bfe_u32 v2, v2, s55, 8
	v_lshl_add_u32 v2, v2, 2, v144
	ds_add_u32 v2, v192
	s_or_b64 exec, exec, s[0:1]
	v_add_f32_e32 v2, 0, v120
	v_ashrrev_i32_e32 v3, 31, v2
	v_bitop3_b32 v2, v3, v2, s96 bitop3:0x36
	v_lshrrev_b32_e32 v3, s33, v2
	v_cmp_eq_u32_e32 vcc, v3, v94
	v_or_b32_e32 v3, v31, v78
	v_cmp_le_i32_e64 s[0:1], v3, v30
	s_and_b64 s[18:19], vcc, s[0:1]
	s_and_saveexec_b64 s[0:1], s[18:19]
	v_bfe_u32 v2, v2, s55, 8
	v_lshl_add_u32 v2, v2, 2, v144
	ds_add_u32 v2, v192
	s_or_b64 exec, exec, s[0:1]
	v_add_f32_e32 v2, 0, v121
	v_ashrrev_i32_e32 v3, 31, v2
	v_bitop3_b32 v2, v3, v2, s96 bitop3:0x36
	v_lshrrev_b32_e32 v3, s33, v2
	v_cmp_eq_u32_e32 vcc, v3, v94
	v_or_b32_e32 v3, v31, v71
	v_cmp_le_i32_e64 s[0:1], v3, v30
	s_and_b64 s[18:19], vcc, s[0:1]
	s_and_saveexec_b64 s[0:1], s[18:19]
	v_bfe_u32 v2, v2, s55, 8
	v_lshl_add_u32 v2, v2, 2, v144
	ds_add_u32 v2, v192
	s_or_b64 exec, exec, s[0:1]
	v_add_f32_e32 v2, 0, v118
	v_ashrrev_i32_e32 v3, 31, v2
	v_bitop3_b32 v2, v3, v2, s96 bitop3:0x36
	v_lshrrev_b32_e32 v3, s33, v2
	v_cmp_eq_u32_e32 vcc, v3, v94
	v_or_b32_e32 v3, v31, v80
	v_cmp_le_i32_e64 s[0:1], v3, v30
	s_and_b64 s[18:19], vcc, s[0:1]
	s_and_saveexec_b64 s[0:1], s[18:19]
	v_bfe_u32 v2, v2, s55, 8
	v_lshl_add_u32 v2, v2, 2, v144
	ds_add_u32 v2, v192
	s_or_b64 exec, exec, s[0:1]
	v_add_f32_e32 v2, 0, v119
	v_ashrrev_i32_e32 v3, 31, v2
	v_bitop3_b32 v2, v3, v2, s96 bitop3:0x36
	v_lshrrev_b32_e32 v3, s33, v2
	v_cmp_eq_u32_e32 vcc, v3, v94
	v_or_b32_e32 v3, v31, v75
	v_cmp_le_i32_e64 s[0:1], v3, v30
	s_and_b64 s[18:19], vcc, s[0:1]
	s_and_saveexec_b64 s[0:1], s[18:19]
	v_bfe_u32 v2, v2, s55, 8
	v_lshl_add_u32 v2, v2, 2, v144
	ds_add_u32 v2, v192
	s_or_b64 exec, exec, s[0:1]
	v_add_f32_e32 v2, 0, v116
	v_ashrrev_i32_e32 v3, 31, v2
	v_bitop3_b32 v2, v3, v2, s96 bitop3:0x36
	v_lshrrev_b32_e32 v3, s33, v2
	v_cmp_eq_u32_e32 vcc, v3, v94
	v_or_b32_e32 v3, v31, v82
	v_cmp_le_i32_e64 s[0:1], v3, v30
	s_and_b64 s[18:19], vcc, s[0:1]
	s_and_saveexec_b64 s[0:1], s[18:19]
	v_bfe_u32 v2, v2, s55, 8
	v_lshl_add_u32 v2, v2, 2, v144
	ds_add_u32 v2, v192
	s_or_b64 exec, exec, s[0:1]
	v_add_f32_e32 v2, 0, v117
	v_ashrrev_i32_e32 v3, 31, v2
	v_bitop3_b32 v2, v3, v2, s96 bitop3:0x36
	v_lshrrev_b32_e32 v3, s33, v2
	v_cmp_eq_u32_e32 vcc, v3, v94
	v_or_b32_e32 v3, v31, v77
	v_cmp_le_i32_e64 s[0:1], v3, v30
	s_and_b64 s[18:19], vcc, s[0:1]
	s_and_saveexec_b64 s[0:1], s[18:19]
	v_bfe_u32 v2, v2, s55, 8
	v_lshl_add_u32 v2, v2, 2, v144
	ds_add_u32 v2, v192
	s_or_b64 exec, exec, s[0:1]
	v_add_f32_e32 v2, 0, v114
	v_ashrrev_i32_e32 v3, 31, v2
	v_bitop3_b32 v2, v3, v2, s96 bitop3:0x36
	v_lshrrev_b32_e32 v3, s33, v2
	v_cmp_eq_u32_e32 vcc, v3, v94
	v_or_b32_e32 v3, v31, v84
	v_cmp_le_i32_e64 s[0:1], v3, v30
	s_and_b64 s[18:19], vcc, s[0:1]
	s_and_saveexec_b64 s[0:1], s[18:19]
	v_bfe_u32 v2, v2, s55, 8
	v_lshl_add_u32 v2, v2, 2, v144
	ds_add_u32 v2, v192
	s_or_b64 exec, exec, s[0:1]
	v_add_f32_e32 v2, 0, v115
	v_ashrrev_i32_e32 v3, 31, v2
	v_bitop3_b32 v2, v3, v2, s96 bitop3:0x36
	v_lshrrev_b32_e32 v3, s33, v2
	v_cmp_eq_u32_e32 vcc, v3, v94
	v_or_b32_e32 v3, v31, v79
	v_cmp_le_i32_e64 s[0:1], v3, v30
	s_and_b64 s[18:19], vcc, s[0:1]
	s_and_saveexec_b64 s[0:1], s[18:19]
	v_bfe_u32 v2, v2, s55, 8
	v_lshl_add_u32 v2, v2, 2, v144
	ds_add_u32 v2, v192
	s_or_b64 exec, exec, s[0:1]
	v_add_f32_e32 v2, 0, v112
	v_ashrrev_i32_e32 v3, 31, v2
	v_bitop3_b32 v2, v3, v2, s96 bitop3:0x36
	v_lshrrev_b32_e32 v3, s33, v2
	v_cmp_eq_u32_e32 vcc, v3, v94
	v_or_b32_e32 v3, v31, v86
	v_cmp_le_i32_e64 s[0:1], v3, v30
	s_and_b64 s[18:19], vcc, s[0:1]
	s_and_saveexec_b64 s[0:1], s[18:19]
	v_bfe_u32 v2, v2, s55, 8
	v_lshl_add_u32 v2, v2, 2, v144
	ds_add_u32 v2, v192
	s_or_b64 exec, exec, s[0:1]
	v_add_f32_e32 v2, 0, v113
	v_ashrrev_i32_e32 v3, 31, v2
	v_bitop3_b32 v2, v3, v2, s96 bitop3:0x36
	v_lshrrev_b32_e32 v3, s33, v2
	v_cmp_eq_u32_e32 vcc, v3, v94
	v_or_b32_e32 v3, v31, v81
	v_cmp_le_i32_e64 s[0:1], v3, v30
	s_and_b64 s[18:19], vcc, s[0:1]
	s_and_saveexec_b64 s[0:1], s[18:19]
	v_bfe_u32 v2, v2, s55, 8
	v_lshl_add_u32 v2, v2, 2, v144
	ds_add_u32 v2, v192
	s_or_b64 exec, exec, s[0:1]
	s_mov_b64 s[0:1], 0

; DI void dsa_item(const Params& P, int layer, int b, int qt, char* mb, char* smem) {
;     ...
;   for (int j = 0; j < 8; j++) {
;     const int qq = wave * 8 + j;
;     const int qpos = q0 + qq;
;     const size_t tok = tokb + qpos;
;     const int n = min((int)meta[64 + qq], 256);
;     __syncthreads();
;     bf16x8 qf[4];
; #pragma unroll
;     for (int ks = 0; ks < 4; ks++) qf[ks] = qn[ks];
;     {
;       const size_t tokn = tokb + q0 + wave * 8 + min(j + 1, 7);
; #pragma unroll
;       for (int ks = 0; ks < 4; ks++) {
;         bf16x8 z = {0, 0, 0, 0, 0, 0, 0, 0};
;         if (r < 4) z = *(const bf16x8*)(Qs + tokn * 256 + r * 64 + ks * 16 + hh * 8);
;         qn[ks] = z;
;       }
;     }
.LBB0_4012:
	v_or_b32_e32 v52, s14, v140
	v_lshl_add_u32 v2, v52, 2, 0
	ds_read_b32 v53, v2 offset:49536
	s_add_i32 s14, s14, 1
	s_min_i32 s12, s14, 7
	v_or_b32_e32 v2, s12, v142
	v_mov_b32_e32 v3, v143
	v_lshlrev_b64 v[2:3], 9, v[2:3]
	v_lshl_add_u64 v[2:3], v[144:145], 0, v[2:3]
	v_mov_b32_e32 v18, 0
	v_mov_b32_e32 v22, 0
	v_mov_b32_e32 v23, 0
	v_mov_b32_e32 v24, 0
	v_mov_b32_e32 v25, 0
	s_waitcnt lgkmcnt(0)
	s_and_saveexec_b64 s[12:13], s[4:5]
	s_cbranch_execz .LBB0_4014
	global_load_dwordx4 v[22:25], v[2:3], off

; DI void dsa_item(const Params& P, int layer, int b, int qt, char* mb, char* smem) {
;     ...
;     __syncthreads();
;     float sc[4][4];
; #pragma unroll
;     for (int rd = 0; rd < 4; rd++) {
;       const int jj = rd * 64 + lane;
;       const bool valid = jj < n;
;       const int kidx = valid ? (int)sidx[qq * 256 + jj] : 0;
;       const int dist = min(max(qpos - kidx, 0), 128);
;       const float4 d = *(const float4*)(myP + jj * 4);
;       sc[rd][0] = valid ? d.x * 0.125f + sbias[0 * 129 + dist] : -INFINITY;
;       sc[rd][1] = valid ? d.y * 0.125f + sbias[1 * 129 + dist] : -INFINITY;
;       sc[rd][2] = valid ? d.z * 0.125f + sbias[2 * 129 + dist] : -INFINITY;
;       sc[rd][3] = valid ? d.w * 0.125f + sbias[3 * 129 + dist] : -INFINITY;
;     }
.LBB0_4038:
	s_nop 3
	v_lshlrev_b32_e32 v3, 8, v52
	v_cmp_gt_i32_e32 vcc, v53, v205
	v_mov_b32_e32 v2, 0
	v_lshl_add_u32 v12, v3, 1, v215
	s_waitcnt lgkmcnt(0)
	s_and_saveexec_b64 s[12:13], vcc
	ds_read_u16 v2, v12 offset:32896
	s_or_b64 exec, exec, s[12:13]
	ds_read2_b32 v[4:5], v220 offset0:1 offset1:2
	ds_read_b32 v6, v220 offset:12
	v_add_u32_e32 v156, s56, v52
	s_waitcnt lgkmcnt(2)
	v_sub_u32_e32 v2, v156, v2
	v_med3_i32 v3, v2, 0, v204
	v_mov_b32_e32 v2, 0xff800000
	v_lshl_add_u32 v7, v3, 2, 0
	v_mov_b32_e32 v10, 0xff800000
	s_and_saveexec_b64 s[12:13], vcc
	s_cbranch_execz .LBB0_4096
	ds_read_b32 v3, v220
	ds_read_b32 v10, v7 offset:50304
	s_waitcnt lgkmcnt(0)
	v_fmac_f32_e32 v10, 0x3e000000, v3
	s_or_b64 exec, exec, s[12:13]
	v_mov_b32_e32 v3, 0xff800000
	s_and_saveexec_b64 s[12:13], vcc
	s_cbranch_execnz .LBB0_4097

; DI float wave_sum(float v) { for (int o = 32; o > 0; o >>= 1) v += __shfl_xor(v, o); return v; }
; DI float wave_max(float v) { for (int o = 32; o > 0; o >>= 1) v = fmaxf(v, __shfl_xor(v, o)); return v; }
; DI void dsa_item(const Params& P, int layer, int b, int qt, char* mb, char* smem) {
;     ...
; #pragma unroll
;     for (int hd = 0; hd < 4; hd++) {
;       float mx = fmaxf(fmaxf(sc[0][hd], sc[1][hd]), fmaxf(sc[2][hd], sc[3][hd]));
;       mx = wave_max(mx);
;       float sm = 0.f;
; #pragma unroll
;       for (int rd = 0; rd < 4; rd++) { sc[rd][hd] = __expf(sc[rd][hd] - mx); sm += sc[rd][hd]; }
;       sm = wave_sum(sm);
;       const float inv = 1.f / sm;
; #pragma unroll
;       for (int rd = 0; rd < 4; rd++) sc[rd][hd] *= inv;
;     }
.LBB0_4062:
	s_or_b64 exec, exec, s[12:13]
	s_waitcnt lgkmcnt(1)
	v_max_f32_e32 v8, v15, v15
	v_max_f32_e32 v9, v13, v13
	v_max_f32_e32 v8, v9, v8
	v_max3_f32 v8, v10, v11, v8
	ds_bpermute_b32 v9, v1, v8
	s_waitcnt lgkmcnt(1)
	v_max_f32_e32 v12, v16, v16
	v_max_f32_e32 v14, v6, v6
	v_max_f32_e32 v12, v14, v12
	v_max3_f32 v12, v2, v4, v12
	s_waitcnt lgkmcnt(0)
	v_max_f32_e32 v9, v9, v9
	v_max_f32_e32 v8, v8, v9
	ds_bpermute_b32 v9, v141, v8
	ds_bpermute_b32 v14, v1, v12
	v_mov_b32_e32 v174, 0
	s_mov_b32 s15, 0
	v_mov_b32_e32 v153, v219
	s_waitcnt lgkmcnt(1)
	v_max_f32_e32 v9, v9, v9
	v_max_f32_e32 v8, v8, v9
	ds_bpermute_b32 v9, v207, v8
	s_waitcnt lgkmcnt(1)
	v_max_f32_e32 v14, v14, v14
	v_max_f32_e32 v12, v12, v14
	ds_bpermute_b32 v14, v141, v12
	v_mov_b32_e32 v155, v218
	s_waitcnt lgkmcnt(1)
	v_max_f32_e32 v9, v9, v9
	v_max_f32_e32 v8, v8, v9
	ds_bpermute_b32 v9, v208, v8
	s_waitcnt lgkmcnt(1)
	v_max_f32_e32 v14, v14, v14
	v_max_f32_e32 v12, v12, v14
	ds_bpermute_b32 v14, v207, v12
	v_mov_b32_e32 v175, v174
	s_waitcnt lgkmcnt(1)
	v_max_f32_e32 v9, v9, v9
	v_max_f32_e32 v8, v8, v9
	ds_bpermute_b32 v9, v209, v8
	s_waitcnt lgkmcnt(1)
	v_max_f32_e32 v14, v14, v14
	v_max_f32_e32 v12, v12, v14
	ds_bpermute_b32 v14, v208, v12
	v_mov_b32_e32 v180, v174
	s_waitcnt lgkmcnt(1)
	v_max_f32_e32 v9, v9, v9
	v_max_f32_e32 v8, v8, v9
	ds_bpermute_b32 v9, v210, v8
	s_waitcnt lgkmcnt(1)
	v_max_f32_e32 v14, v14, v14
	v_max_f32_e32 v39, v12, v14
	ds_bpermute_b32 v12, v209, v39
	v_mov_b32_e32 v181, v174
	s_waitcnt lgkmcnt(1)
	v_max_f32_e32 v9, v9, v9
	v_max_f32_e32 v8, v8, v9
	v_sub_f32_e32 v9, v10, v8
	s_waitcnt lgkmcnt(0)
	v_max_f32_e32 v40, v12, v12
	v_mul_f32_e32 v9, 0x3fb8aa3b, v9
	v_exp_f32_e32 v14, v9
	v_max_f32_e32 v9, v39, v40
	v_sub_f32_e32 v10, v11, v8
	v_sub_f32_e32 v11, v13, v8
	ds_bpermute_b32 v13, v210, v9
	v_mul_f32_e32 v10, 0x3fb8aa3b, v10
	v_mul_f32_e32 v11, 0x3fb8aa3b, v11
	v_exp_f32_e32 v12, v10
	v_exp_f32_e32 v10, v11
	v_sub_f32_e32 v8, v15, v8
	s_waitcnt lgkmcnt(0)
	v_max_f32_e32 v11, v13, v13
	v_max_f32_e32 v13, v17, v17
	v_max_f32_e32 v15, v7, v7
	v_max_f32_e32 v13, v15, v13
	v_max3_f32 v13, v3, v5, v13
	ds_bpermute_b32 v39, v1, v13
	v_max_f32_e32 v9, v9, v11
	v_sub_f32_e32 v2, v2, v9
	v_mul_f32_e32 v2, 0x3fb8aa3b, v2
	v_exp_f32_e32 v15, v2
	s_waitcnt lgkmcnt(0)
	v_max_f32_e32 v2, v39, v39
	v_max_f32_e32 v2, v13, v2
	ds_bpermute_b32 v11, v141, v2
	v_sub_f32_e32 v4, v4, v9
	v_mul_f32_e32 v4, 0x3fb8aa3b, v4
	v_exp_f32_e32 v13, v4
	v_sub_f32_e32 v6, v6, v9
	s_waitcnt lgkmcnt(0)
	v_max_f32_e32 v4, v11, v11
	v_max_f32_e32 v2, v2, v4
	ds_bpermute_b32 v4, v207, v2
	v_mul_f32_e32 v6, 0x3fb8aa3b, v6
	v_exp_f32_e32 v11, v6
	v_sub_f32_e32 v6, v16, v9
	v_max_f32_e32 v9, v38, v38
	s_waitcnt lgkmcnt(0)
	v_max_f32_e32 v4, v4, v4
	v_max_f32_e32 v2, v2, v4
	v_max_f32_e32 v16, v37, v37
	ds_bpermute_b32 v4, v208, v2
	v_max_f32_e32 v9, v16, v9
	v_max3_f32 v9, v34, v36, v9
	ds_bpermute_b32 v16, v1, v9
	v_mul_f32_e32 v6, 0x3fb8aa3b, v6
	s_waitcnt lgkmcnt(1)
	v_max_f32_e32 v4, v4, v4
	v_max_f32_e32 v2, v2, v4
	ds_bpermute_b32 v4, v209, v2
	s_waitcnt lgkmcnt(1)
	v_max_f32_e32 v16, v16, v16
	v_max_f32_e32 v16, v9, v16
	ds_bpermute_b32 v39, v141, v16
	v_exp_f32_e32 v9, v6
	s_waitcnt lgkmcnt(1)
	v_max_f32_e32 v4, v4, v4
	v_max_f32_e32 v2, v2, v4
	ds_bpermute_b32 v4, v210, v2
	s_waitcnt lgkmcnt(1)
	v_max_f32_e32 v6, v39, v39
	v_max_f32_e32 v6, v16, v6
	ds_bpermute_b32 v16, v207, v6
	v_mul_f32_e32 v8, 0x3fb8aa3b, v8
	s_waitcnt lgkmcnt(1)
	v_max_f32_e32 v4, v4, v4
	v_max_f32_e32 v39, v2, v4
	v_sub_f32_e32 v2, v3, v39
	s_waitcnt lgkmcnt(0)
	v_max_f32_e32 v3, v16, v16
	v_max_f32_e32 v3, v6, v3
	ds_bpermute_b32 v16, v208, v3
	v_mul_f32_e32 v2, 0x3fb8aa3b, v2
	v_exp_f32_e32 v4, v2
	v_sub_f32_e32 v2, v5, v39
	v_exp_f32_e32 v8, v8
	v_mul_f32_e32 v2, 0x3fb8aa3b, v2
	v_pk_add_f32 v[40:41], v[14:15], 0 op_sel_hi:[1,0]
	v_exp_f32_e32 v6, v2
	s_waitcnt lgkmcnt(0)
	v_max_f32_e32 v2, v16, v16
	v_max_f32_e32 v5, v3, v2
	v_pk_add_f32 v[2:3], v[12:13], v[40:41]
	ds_bpermute_b32 v16, v209, v5
	v_pk_add_f32 v[2:3], v[10:11], v[2:3]
	v_sub_f32_e32 v7, v7, v39
	v_pk_add_f32 v[2:3], v[8:9], v[2:3]
	ds_bpermute_b32 v40, v1, v2
	ds_bpermute_b32 v41, v1, v3
	s_waitcnt lgkmcnt(2)
	v_max_f32_e32 v16, v16, v16
	v_max_f32_e32 v5, v5, v16
	ds_bpermute_b32 v42, v210, v5
	v_mul_f32_e32 v7, 0x3fb8aa3b, v7
	s_waitcnt lgkmcnt(1)
	v_pk_add_f32 v[2:3], v[2:3], v[40:41]
	ds_bpermute_b32 v40, v141, v2
	ds_bpermute_b32 v41, v141, v3
	v_exp_f32_e32 v16, v7
	v_sub_f32_e32 v7, v17, v39
	s_waitcnt lgkmcnt(2)
	v_max_f32_e32 v17, v42, v42
	v_max_f32_e32 v39, v5, v17
	s_waitcnt lgkmcnt(0)
; DI float wave_sum(float v) { for (int o = 32; o > 0; o >>= 1) v += __shfl_xor(v, o); return v; }
; DI void dsa_item(const Params& P, int layer, int b, int qt, char* mb, char* smem) {
;     ...
;       for (int rd = 0; rd < 4; rd++) { sc[rd][hd] = __expf(sc[rd][hd] - mx); sm += sc[rd][hd]; }
;       sm = wave_sum(sm);
;       const float inv = 1.f / sm;
; #pragma unroll
;       for (int rd = 0; rd < 4; rd++) sc[rd][hd] *= inv;
;     }
; #pragma unroll
;     for (int rd = 0; rd < 4; rd++) *(float4*)(myP + (rd * 64 + lane) * 4) = make_float4(sc[rd][0], sc[rd][1], sc[rd][2], sc[rd][3]);
;     __syncthreads();
;     const int g = lane >> 3, c8 = lane & 7;
;     float acc[32];
; #pragma unroll
;     for (int i = 0; i < 32; i++) acc[i] = 0.f;
	v_pk_add_f32 v[2:3], v[2:3], v[40:41]
	ds_bpermute_b32 v40, v207, v2
	ds_bpermute_b32 v41, v207, v3
	v_sub_f32_e32 v5, v34, v39
	v_mul_f32_e32 v7, 0x3fb8aa3b, v7
	v_mul_f32_e32 v5, 0x3fb8aa3b, v5
	v_exp_f32_e32 v42, v7
	s_waitcnt lgkmcnt(0)
	v_pk_add_f32 v[2:3], v[2:3], v[40:41]
	ds_bpermute_b32 v40, v208, v2
	ds_bpermute_b32 v41, v208, v3
	v_sub_f32_e32 v7, v36, v39
	v_exp_f32_e32 v5, v5
	v_mul_f32_e32 v7, 0x3fb8aa3b, v7
	v_sub_f32_e32 v17, v37, v39
	s_waitcnt lgkmcnt(0)
	v_pk_add_f32 v[2:3], v[2:3], v[40:41]
	ds_bpermute_b32 v40, v209, v2
	ds_bpermute_b32 v41, v209, v3
	v_exp_f32_e32 v7, v7
	v_mul_f32_e32 v17, 0x3fb8aa3b, v17
	v_sub_f32_e32 v34, v38, v39
	v_exp_f32_e32 v17, v17
	s_waitcnt lgkmcnt(0)
	v_pk_add_f32 v[2:3], v[2:3], v[40:41]
	ds_bpermute_b32 v36, v210, v2
	ds_bpermute_b32 v37, v210, v3
	v_mul_f32_e32 v34, 0x3fb8aa3b, v34
	v_exp_f32_e32 v43, v34
	v_pk_add_f32 v[44:45], v[4:5], 0 op_sel_hi:[1,0]
	v_mov_b32_e32 v162, v174
	s_waitcnt lgkmcnt(0)
	v_pk_add_f32 v[2:3], v[2:3], v[36:37]
	v_pk_add_f32 v[36:37], v[6:7], v[44:45]
	v_div_scale_f32 v34, s[12:13], v3, v3, 1.0
	v_pk_add_f32 v[36:37], v[16:17], v[36:37]
	v_rcp_f32_e32 v40, v34
	v_pk_add_f32 v[36:37], v[42:43], v[36:37]
	ds_bpermute_b32 v38, v1, v36
	ds_bpermute_b32 v39, v1, v37
	v_fma_f32 v41, -v34, v40, 1.0
	v_fmac_f32_e32 v40, v41, v40
	v_div_scale_f32 v41, vcc, 1.0, v3, 1.0
	s_waitcnt lgkmcnt(0)
	v_pk_add_f32 v[36:37], v[36:37], v[38:39]
	ds_bpermute_b32 v38, v141, v36
	ds_bpermute_b32 v39, v141, v37
	v_mul_f32_e32 v44, v41, v40
	v_fma_f32 v45, -v34, v44, v41
	v_fmac_f32_e32 v44, v45, v40
	v_fma_f32 v34, -v34, v44, v41
	s_waitcnt lgkmcnt(0)
	v_pk_add_f32 v[36:37], v[36:37], v[38:39]
	ds_bpermute_b32 v38, v207, v36
	ds_bpermute_b32 v39, v207, v37
	v_div_fmas_f32 v34, v34, v40, v44
	v_div_fixup_f32 v41, v34, v3, 1.0
	v_div_scale_f32 v3, s[12:13], v2, v2, 1.0
	s_waitcnt lgkmcnt(0)
	v_pk_add_f32 v[36:37], v[36:37], v[38:39]
	ds_bpermute_b32 v38, v208, v36
	ds_bpermute_b32 v39, v208, v37
	v_rcp_f32_e32 v34, v3
	v_mov_b32_e32 v163, v174
	v_mov_b32_e32 v164, v174
	v_mov_b32_e32 v165, v174
	s_waitcnt lgkmcnt(0)
	v_pk_add_f32 v[36:37], v[36:37], v[38:39]
	ds_bpermute_b32 v38, v209, v36
	ds_bpermute_b32 v39, v209, v37
	v_fma_f32 v40, -v3, v34, 1.0
	v_fmac_f32_e32 v34, v40, v34
	v_div_scale_f32 v40, vcc, 1.0, v2, 1.0
	s_waitcnt lgkmcnt(0)
	v_pk_add_f32 v[36:37], v[36:37], v[38:39]
	ds_bpermute_b32 v38, v210, v36
	ds_bpermute_b32 v39, v210, v37
	v_mul_f32_e32 v44, v40, v34
	v_fma_f32 v45, -v3, v44, v40
	v_fmac_f32_e32 v44, v45, v34
	v_fma_f32 v3, -v3, v44, v40
	s_waitcnt lgkmcnt(0)
	v_pk_add_f32 v[36:37], v[36:37], v[38:39]
	v_div_fmas_f32 v3, v3, v34, v44
	v_div_scale_f32 v38, s[12:13], v37, v37, 1.0
	v_rcp_f32_e32 v39, v38
	v_div_fixup_f32 v40, v3, v2, 1.0
	v_pk_mul_f32 v[2:3], v[14:15], v[40:41]
	v_mov_b32_e32 v170, v174
	v_fma_f32 v14, -v38, v39, 1.0
	v_fmac_f32_e32 v39, v14, v39
	v_div_scale_f32 v14, vcc, 1.0, v37, 1.0
	v_mul_f32_e32 v15, v14, v39
	v_fma_f32 v34, -v38, v15, v14
	v_fmac_f32_e32 v15, v34, v39
	v_div_scale_f32 v34, s[12:13], v36, v36, 1.0
	v_fma_f32 v14, -v38, v15, v14
	v_rcp_f32_e32 v38, v34
	v_div_fmas_f32 v14, v14, v39, v15
	v_div_fixup_f32 v15, v14, v37, 1.0
	v_mov_b32_e32 v171, v174
	v_fma_f32 v14, -v34, v38, 1.0
	v_fmac_f32_e32 v38, v14, v38
	v_div_scale_f32 v14, vcc, 1.0, v36, 1.0
	v_mul_f32_e32 v37, v14, v38
	v_fma_f32 v39, -v34, v37, v14
	v_fmac_f32_e32 v37, v39, v38
	v_fma_f32 v14, -v34, v37, v14
	v_div_fmas_f32 v14, v14, v38, v37
	v_div_fixup_f32 v14, v14, v36, 1.0
	v_pk_mul_f32 v[4:5], v[4:5], v[14:15]
	ds_write_b128 v220, v[2:5]
	v_pk_mul_f32 v[2:3], v[12:13], v[40:41]
	v_pk_mul_f32 v[4:5], v[6:7], v[14:15]
	ds_write_b128 v220, v[2:5] offset:1024
	v_pk_mul_f32 v[2:3], v[10:11], v[40:41]
	v_pk_mul_f32 v[4:5], v[16:17], v[14:15]
	ds_write_b128 v220, v[2:5] offset:2048
	v_pk_mul_f32 v[2:3], v[8:9], v[40:41]
	v_pk_mul_f32 v[4:5], v[42:43], v[14:15]
	v_mov_b32_e32 v172, v174
	v_mov_b32_e32 v173, v174
	v_mov_b32_e32 v158, v174
	v_mov_b32_e32 v159, v174
	v_mov_b32_e32 v160, v174
	v_mov_b32_e32 v161, v174
	v_mov_b32_e32 v188, v174
	v_mov_b32_e32 v189, v174
	v_mov_b32_e32 v190, v174
	v_mov_b32_e32 v191, v174
	v_mov_b32_e32 v176, v174
	v_mov_b32_e32 v177, v174
	v_mov_b32_e32 v178, v174
	v_mov_b32_e32 v179, v174
	v_mov_b32_e32 v182, v174
	v_mov_b32_e32 v183, v174
	v_mov_b32_e32 v186, v174
	v_mov_b32_e32 v187, v174
	v_mov_b32_e32 v166, v174
	v_mov_b32_e32 v167, v174
	v_mov_b32_e32 v168, v174
	v_mov_b32_e32 v169, v174
	ds_write_b128 v220, v[2:5] offset:3072
	s_waitcnt lgkmcnt(0)
	s_branch .LBB0_4064

; DI char* WS(const Params& P) { return P.ws + opaque0(); }
; DI void da_item(const Params& P, int layer, int b, int h, int qt, char* mb, char* smem) {
;     ...
;   __syncthreads();
;   if (tid < 129) sbias[tid] = ((const float*)(WS(P) + OFF_BIAS))[h * 129 + tid] * LOG2E_;
;   __syncthreads();
; DI void phase_mix1(const Params& P, int layer, int bid, int nb, char* smem) {
;     ...
;   for (int j = 0;; j++) {
;     const int idx = (j & 1) ? (j * nb + (nb - 1 - bid)) : (j * nb + bid);
;     if (j * nb >= 2048) break;
;     if (idx >= 2048) continue;
;     const int qt = 63 - (idx >> 5), bh = idx & 31;
;     da_item(P, layer, bh >> 2, bh & 3, qt, mb, smem);
.LBB0_4111:
	s_waitcnt vmcnt(0) lgkmcnt(0)
	s_barrier
	v_readlane_b32 s4, v237, 9
	v_readlane_b32 s5, v237, 10
	s_mov_b64 s[22:23], exec
	s_and_b64 s[4:5], s[22:23], s[4:5]
	s_mov_b64 exec, s[4:5]
	s_cbranch_execz .Lq_da0_skip
	v_readlane_b32 s4, v237, 0
	v_readlane_b32 s5, v237, 1
	s_add_u32 s4, s4, 0x55891c0
	s_addc_u32 s5, s5, 0
	v_mov_b32_e32 v238, 0
	v_mov_b32_e32 v239, 1
	global_atomic_add v239, v238, v239, s[4:5] sc0
	v_mov_b32_e32 v238, 0x11ff8
	s_waitcnt vmcnt(0)
	ds_write_b32 v238, v239
.Lq_da0_skip:
	s_mov_b64 exec, s[22:23]
	s_waitcnt lgkmcnt(0)
	s_barrier
	v_mov_b32_e32 v238, 0x11ff8
	ds_read_b32 v238, v238
	s_waitcnt lgkmcnt(0)
	s_nop 0
	v_readfirstlane_b32 s10, v238
	s_mov_b32 s28, s10
	s_mov_b32 s38, 0
	s_cmpk_gt_i32 s10, 0x7ff
	s_mov_b32 s24, 8
	s_cbranch_scc1 .LBB0_4134
	v_mov_b32_e32 v3, v202
	s_and_b32 s24, s10, 3
	v_mov_b32_e32 v1, v202
	s_mov_b64 s[4:5], 0
	v_cmp_gt_i32_e32 vcc, s3, v3
	s_waitcnt vmcnt(0) lgkmcnt(0)
	s_barrier
	s_and_saveexec_b64 s[22:23], vcc
	s_cbranch_execz .LBB0_4115
	s_mov_b64 s[26:27], 0
	v_readlane_b32 s30, v237, 0
	s_mul_i32 s25, s24, 0x81
	v_readlane_b32 s31, v237, 1
	s_add_u32 s26, s30, s26
	v_add_u32_e32 v4, s25, v3
	s_addc_u32 s27, s31, s27
	v_ashrrev_i32_e32 v5, 31, v4
	v_lshl_add_u64 v[4:5], v[4:5], 2, s[26:27]
	v_add_co_u32_e32 v4, vcc, 0x5588000, v4
	s_nop 1
	v_addc_co_u32_e32 v5, vcc, 0, v5, vcc
	global_load_dword v4, v[4:5], off offset:256
	v_lshl_add_u32 v5, v3, 2, 0
	s_waitcnt vmcnt(0)
	v_mul_f32_e32 v4, 0x3fb8aa3b, v4
	ds_write_b32 v5, v4 offset:53248

; DI char* WS(const Params& P) { return P.ws + opaque0(); }
; DI void dsa_item(const Params& P, int layer, int b, int qt, char* mb, char* smem) {
;     ...
;   __syncthreads();
;   for (int i = tid; i < 4 * 129; i += 256) sbias[i] = ((const float*)(WS(P) + OFF_BIAS))[4 * 129 + i];
; DI void phase_mix1(const Params& P, int layer, int bid, int nb, char* smem) {
;     ...
;   for (int j = 0;; j++) {
;     const int idx = (j & 1) ? (j * nb + (nb - 1 - bid)) : (j * nb + bid);
;     if (j * nb >= 2048) break;
;     if (idx >= 2048) continue;
;     const int qt = 255 - (idx >> 3), b = idx & 7;
;     dsa_item(P, layer, b, qt, mb, smem);
.LBB0_7186:
	s_waitcnt vmcnt(0) lgkmcnt(0)
	s_barrier
	v_readlane_b32 s4, v237, 9
	v_readlane_b32 s5, v237, 10
	s_mov_b64 s[0:1], exec
	s_and_b64 s[4:5], s[0:1], s[4:5]
	s_mov_b64 exec, s[4:5]
	s_cbranch_execz .Lq_dsa1_skip
	v_readlane_b32 s4, v237, 0
	v_readlane_b32 s5, v237, 1
	s_add_u32 s4, s4, 0x5589240
	s_addc_u32 s5, s5, 0
	v_mov_b32_e32 v238, 0
	v_mov_b32_e32 v239, 1
	global_atomic_add v239, v238, v239, s[4:5] sc0
	v_mov_b32_e32 v238, 0x11ff8
	s_waitcnt vmcnt(0)
	ds_write_b32 v238, v239
.Lq_dsa1_skip:
	s_mov_b64 exec, s[0:1]
	s_waitcnt lgkmcnt(0)
	s_barrier
	v_mov_b32_e32 v238, 0x11ff8
	ds_read_b32 v238, v238
	s_waitcnt lgkmcnt(0)
	s_nop 0
	v_readfirstlane_b32 s6, v238
	s_cmpk_gt_i32 s6, 0x7ff
	s_mov_b32 s7, 5
	s_cbranch_scc1 .LBB0_8064
	v_mov_b32_e32 v68, v202
	s_movk_i32 s0, 0x203
	s_mov_b64 s[68:69], 0
	v_cmp_lt_i32_e32 vcc, s0, v68
	v_ashrrev_i32_e32 v69, 31, v68
	s_waitcnt vmcnt(0)
	v_add_u32_e32 v131, 0xffffff00, v68
	v_lshlrev_b32_e32 v85, 2, v68
	s_waitcnt lgkmcnt(0)
	s_barrier
	s_and_saveexec_b64 s[0:1], vcc
	s_xor_b64 s[0:1], exec, s[0:1]
	v_add_u32_e32 v131, 0xffffff00, v68
	v_lshlrev_b32_e32 v85, 2, v68
	s_andn2_saveexec_b64 s[0:1], s[0:1]
	s_cbranch_execz .LBB0_7194
	v_readlane_b32 s4, v236, 26
	v_mov_b32_e32 v4, v131
	s_nop 0
	v_add_u32_e32 v1, s4, v85
	v_readlane_b32 s4, v236, 22
	v_readlane_b32 s5, v236, 23
	s_nop 1
	v_lshl_add_u64 v[2:3], v[68:69], 2, s[4:5]
	s_mov_b64 s[4:5], 0

; #define MFMA32(a, b, c) __builtin_amdgcn_mfma_f32_32x32x16_bf16((a), (b), (c), 0, 0, 0)
; DI f32x16 zero16() { f32x16 z; for (int i = 0; i < 16; i++) z[i] = 0.f; return z; }
; DI void dsa_item(const Params& P, int layer, int b, int qt, char* mb, char* smem) {
;     ...
; #pragma unroll 2
;       for (int hd = 0; hd < 8; hd++) {
;         const bf16x8 q0f = *(const bf16x8*)(sQi + r * 528 + hd * 64 + hh * 16);
;         const bf16x8 q1f = *(const bf16x8*)(sQi + r * 528 + hd * 64 + 32 + hh * 16);
;         const float w = sWi[hd * 32 + r];
;         f32x16 sa = MFMA32(kA0, q0f, zero16());
;         f32x16 sb = MFMA32(kB0, q0f, zero16());
;         sa = MFMA32(kA1, q1f, sa);
;         sb = MFMA32(kB1, q1f, sb);
; #pragma unroll
;         for (int i = 0; i < 16; i++) {
;           scA[i] += __int_as_float(max(__float_as_int(sa[i]), 0)) * w;
;           scB[i] += __int_as_float(max(__float_as_int(sb[i]), 0)) * w;
;         }
;       }
.LBB0_7205:
	v_add_u32_e32 v153, 0xffffff80, v148
	ds_read_b128 v[228:231], v147
	ds_read_b128 v[232:235], v147 offset:32
	ds_read_b32 v238, v153
	s_waitcnt lgkmcnt(2)
	v_mfma_f32_32x32x16_bf16 v[2:17], v[64:67], v[228:231], 0
	v_mfma_f32_32x32x16_bf16 v[18:33], v[56:59], v[228:231], 0
	s_waitcnt lgkmcnt(1)
	v_mfma_f32_32x32x16_bf16 v[2:17], v[60:63], v[232:235], v[2:17]
	v_mfma_f32_32x32x16_bf16 v[18:33], v[52:55], v[232:235], v[18:33]
	ds_read_b128 v[228:231], v147 offset:64
	ds_read_b128 v[232:235], v147 offset:96
	ds_read_b32 v239, v153 offset:128
	s_waitcnt lgkmcnt(1)
	v_mfma_f32_32x32x16_bf16 v[240:255], v[64:67], v[228:231], 0
	v_mfma_f32_32x32x16_bf16 v[240:255], v[60:63], v[232:235], v[240:255]
	v_max_i32_e32 v2, 0, v2
	v_fmac_f32_e32 v126, v238, v2
	v_max_i32_e32 v3, 0, v3
	v_fmac_f32_e32 v127, v238, v3
	v_max_i32_e32 v4, 0, v4
	v_fmac_f32_e32 v124, v238, v4
	v_max_i32_e32 v5, 0, v5
	v_fmac_f32_e32 v125, v238, v5
	v_max_i32_e32 v6, 0, v6
	v_fmac_f32_e32 v122, v238, v6
	v_max_i32_e32 v7, 0, v7
	v_fmac_f32_e32 v123, v238, v7
	v_max_i32_e32 v8, 0, v8
	v_fmac_f32_e32 v120, v238, v8
	v_max_i32_e32 v9, 0, v9
	v_fmac_f32_e32 v121, v238, v9
	v_max_i32_e32 v10, 0, v10
	v_fmac_f32_e32 v118, v238, v10
	v_max_i32_e32 v11, 0, v11
	v_fmac_f32_e32 v119, v238, v11
	v_max_i32_e32 v12, 0, v12
	v_fmac_f32_e32 v116, v238, v12
	v_max_i32_e32 v13, 0, v13
	v_fmac_f32_e32 v117, v238, v13
	v_max_i32_e32 v14, 0, v14
	v_fmac_f32_e32 v114, v238, v14
	v_max_i32_e32 v15, 0, v15
	v_fmac_f32_e32 v115, v238, v15
	v_max_i32_e32 v16, 0, v16
	v_fmac_f32_e32 v112, v238, v16
	v_max_i32_e32 v17, 0, v17
	v_fmac_f32_e32 v113, v238, v17
	v_mfma_f32_32x32x16_bf16 v[2:17], v[56:59], v[228:231], 0
	v_mfma_f32_32x32x16_bf16 v[2:17], v[52:55], v[232:235], v[2:17]
	ds_read_b128 v[228:231], v147 offset:128
	ds_read_b128 v[232:235], v147 offset:160
	v_max_i32_e32 v18, 0, v18
	v_fmac_f32_e32 v110, v238, v18
	v_max_i32_e32 v19, 0, v19
	v_fmac_f32_e32 v111, v238, v19
	v_max_i32_e32 v20, 0, v20
	v_fmac_f32_e32 v108, v238, v20
	v_max_i32_e32 v21, 0, v21
	v_fmac_f32_e32 v109, v238, v21
	v_max_i32_e32 v22, 0, v22
	v_fmac_f32_e32 v106, v238, v22
	v_max_i32_e32 v23, 0, v23
	v_fmac_f32_e32 v107, v238, v23
	v_max_i32_e32 v24, 0, v24
	v_fmac_f32_e32 v104, v238, v24
	v_max_i32_e32 v25, 0, v25
	v_fmac_f32_e32 v105, v238, v25
	v_max_i32_e32 v26, 0, v26
	v_fmac_f32_e32 v102, v238, v26
	v_max_i32_e32 v27, 0, v27
	v_fmac_f32_e32 v103, v238, v27
	v_max_i32_e32 v28, 0, v28
	v_fmac_f32_e32 v100, v238, v28
	v_max_i32_e32 v29, 0, v29
	v_fmac_f32_e32 v101, v238, v29
	v_max_i32_e32 v30, 0, v30
	v_fmac_f32_e32 v98, v238, v30
	v_max_i32_e32 v31, 0, v31
	v_fmac_f32_e32 v99, v238, v31
	v_max_i32_e32 v32, 0, v32
	v_fmac_f32_e32 v96, v238, v32
	v_max_i32_e32 v33, 0, v33
	v_fmac_f32_e32 v97, v238, v33
	ds_read_b32 v238, v153 offset:256
	s_waitcnt lgkmcnt(1)
	v_mfma_f32_32x32x16_bf16 v[18:33], v[64:67], v[228:231], 0
	v_mfma_f32_32x32x16_bf16 v[18:33], v[60:63], v[232:235], v[18:33]
	v_max_i32_e32 v240, 0, v240
	v_fmac_f32_e32 v126, v239, v240
	v_max_i32_e32 v241, 0, v241
	v_fmac_f32_e32 v127, v239, v241
	v_max_i32_e32 v242, 0, v242
	v_fmac_f32_e32 v124, v239, v242
	v_max_i32_e32 v243, 0, v243
	v_fmac_f32_e32 v125, v239, v243
	v_max_i32_e32 v244, 0, v244
	v_fmac_f32_e32 v122, v239, v244
	v_max_i32_e32 v245, 0, v245
	v_fmac_f32_e32 v123, v239, v245
	v_max_i32_e32 v246, 0, v246
	v_fmac_f32_e32 v120, v239, v246
	v_max_i32_e32 v247, 0, v247
	v_fmac_f32_e32 v121, v239, v247
	v_max_i32_e32 v248, 0, v248
	v_fmac_f32_e32 v118, v239, v248
	v_max_i32_e32 v249, 0, v249
	v_fmac_f32_e32 v119, v239, v249
	v_max_i32_e32 v250, 0, v250
	v_fmac_f32_e32 v116, v239, v250
	v_max_i32_e32 v251, 0, v251
	v_fmac_f32_e32 v117, v239, v251
	v_max_i32_e32 v252, 0, v252
	v_fmac_f32_e32 v114, v239, v252
	v_max_i32_e32 v253, 0, v253
	v_fmac_f32_e32 v115, v239, v253
	v_max_i32_e32 v254, 0, v254
	v_fmac_f32_e32 v112, v239, v254
	v_max_i32_e32 v255, 0, v255
	v_fmac_f32_e32 v113, v239, v255
	v_mfma_f32_32x32x16_bf16 v[240:255], v[56:59], v[228:231], 0
	v_mfma_f32_32x32x16_bf16 v[240:255], v[52:55], v[232:235], v[240:255]
	ds_read_b128 v[228:231], v147 offset:192
	ds_read_b128 v[232:235], v147 offset:224
	v_max_i32_e32 v2, 0, v2
	v_fmac_f32_e32 v110, v239, v2
	v_max_i32_e32 v3, 0, v3
	v_fmac_f32_e32 v111, v239, v3
	v_max_i32_e32 v4, 0, v4
	v_fmac_f32_e32 v108, v239, v4
	v_max_i32_e32 v5, 0, v5
	v_fmac_f32_e32 v109, v239, v5
	v_max_i32_e32 v6, 0, v6
	v_fmac_f32_e32 v106, v239, v6
	v_max_i32_e32 v7, 0, v7
	v_fmac_f32_e32 v107, v239, v7
	v_max_i32_e32 v8, 0, v8
	v_fmac_f32_e32 v104, v239, v8
	v_max_i32_e32 v9, 0, v9
	v_fmac_f32_e32 v105, v239, v9
	v_max_i32_e32 v10, 0, v10
	v_fmac_f32_e32 v102, v239, v10
	v_max_i32_e32 v11, 0, v11
	v_fmac_f32_e32 v103, v239, v11
	v_max_i32_e32 v12, 0, v12
	v_fmac_f32_e32 v100, v239, v12
	v_max_i32_e32 v13, 0, v13
	v_fmac_f32_e32 v101, v239, v13
	v_max_i32_e32 v14, 0, v14
	v_fmac_f32_e32 v98, v239, v14
	v_max_i32_e32 v15, 0, v15
	v_fmac_f32_e32 v99, v239, v15
	v_max_i32_e32 v16, 0, v16
	v_fmac_f32_e32 v96, v239, v16
	v_max_i32_e32 v17, 0, v17
	v_fmac_f32_e32 v97, v239, v17
	ds_read_b32 v239, v153 offset:384
	s_waitcnt lgkmcnt(1)
; #define MFMA32(a, b, c) __builtin_amdgcn_mfma_f32_32x32x16_bf16((a), (b), (c), 0, 0, 0)
; DI f32x16 zero16() { f32x16 z; for (int i = 0; i < 16; i++) z[i] = 0.f; return z; }
; DI void dsa_item(const Params& P, int layer, int b, int qt, char* mb, char* smem) {
;     ...
; #pragma unroll 2
;       for (int hd = 0; hd < 8; hd++) {
;         const bf16x8 q0f = *(const bf16x8*)(sQi + r * 528 + hd * 64 + hh * 16);
;         const bf16x8 q1f = *(const bf16x8*)(sQi + r * 528 + hd * 64 + 32 + hh * 16);
;         const float w = sWi[hd * 32 + r];
;         f32x16 sa = MFMA32(kA0, q0f, zero16());
;         f32x16 sb = MFMA32(kB0, q0f, zero16());
;         sa = MFMA32(kA1, q1f, sa);
;         sb = MFMA32(kB1, q1f, sb);
; #pragma unroll
;         for (int i = 0; i < 16; i++) {
;           scA[i] += __int_as_float(max(__float_as_int(sa[i]), 0)) * w;
;           scB[i] += __int_as_float(max(__float_as_int(sb[i]), 0)) * w;
;         }
;       }
	v_mfma_f32_32x32x16_bf16 v[2:17], v[64:67], v[228:231], 0
	v_mfma_f32_32x32x16_bf16 v[2:17], v[60:63], v[232:235], v[2:17]
	v_max_i32_e32 v18, 0, v18
	v_fmac_f32_e32 v126, v238, v18
	v_max_i32_e32 v19, 0, v19
	v_fmac_f32_e32 v127, v238, v19
	v_max_i32_e32 v20, 0, v20
	v_fmac_f32_e32 v124, v238, v20
	v_max_i32_e32 v21, 0, v21
	v_fmac_f32_e32 v125, v238, v21
	v_max_i32_e32 v22, 0, v22
	v_fmac_f32_e32 v122, v238, v22
	v_max_i32_e32 v23, 0, v23
	v_fmac_f32_e32 v123, v238, v23
	v_max_i32_e32 v24, 0, v24
	v_fmac_f32_e32 v120, v238, v24
	v_max_i32_e32 v25, 0, v25
	v_fmac_f32_e32 v121, v238, v25
	v_max_i32_e32 v26, 0, v26
	v_fmac_f32_e32 v118, v238, v26
	v_max_i32_e32 v27, 0, v27
	v_fmac_f32_e32 v119, v238, v27
	v_max_i32_e32 v28, 0, v28
	v_fmac_f32_e32 v116, v238, v28
	v_max_i32_e32 v29, 0, v29
	v_fmac_f32_e32 v117, v238, v29
	v_max_i32_e32 v30, 0, v30
	v_fmac_f32_e32 v114, v238, v30
	v_max_i32_e32 v31, 0, v31
	v_fmac_f32_e32 v115, v238, v31
	v_max_i32_e32 v32, 0, v32
	v_fmac_f32_e32 v112, v238, v32
	v_max_i32_e32 v33, 0, v33
	v_fmac_f32_e32 v113, v238, v33
	v_mfma_f32_32x32x16_bf16 v[18:33], v[56:59], v[228:231], 0
	v_mfma_f32_32x32x16_bf16 v[18:33], v[52:55], v[232:235], v[18:33]
	ds_read_b128 v[228:231], v147 offset:256
	ds_read_b128 v[232:235], v147 offset:288
	v_max_i32_e32 v240, 0, v240
	v_fmac_f32_e32 v110, v238, v240
	v_max_i32_e32 v241, 0, v241
	v_fmac_f32_e32 v111, v238, v241
	v_max_i32_e32 v242, 0, v242
	v_fmac_f32_e32 v108, v238, v242
	v_max_i32_e32 v243, 0, v243
	v_fmac_f32_e32 v109, v238, v243
	v_max_i32_e32 v244, 0, v244
	v_fmac_f32_e32 v106, v238, v244
	v_max_i32_e32 v245, 0, v245
	v_fmac_f32_e32 v107, v238, v245
	v_max_i32_e32 v246, 0, v246
	v_fmac_f32_e32 v104, v238, v246
	v_max_i32_e32 v247, 0, v247
	v_fmac_f32_e32 v105, v238, v247
	v_max_i32_e32 v248, 0, v248
	v_fmac_f32_e32 v102, v238, v248
	v_max_i32_e32 v249, 0, v249
	v_fmac_f32_e32 v103, v238, v249
	v_max_i32_e32 v250, 0, v250
	v_fmac_f32_e32 v100, v238, v250
	v_max_i32_e32 v251, 0, v251
	v_fmac_f32_e32 v101, v238, v251
	v_max_i32_e32 v252, 0, v252
	v_fmac_f32_e32 v98, v238, v252
	v_max_i32_e32 v253, 0, v253
	v_fmac_f32_e32 v99, v238, v253
	v_max_i32_e32 v254, 0, v254
	v_fmac_f32_e32 v96, v238, v254
	v_max_i32_e32 v255, 0, v255
	v_fmac_f32_e32 v97, v238, v255
	ds_read_b32 v238, v153 offset:512
	s_waitcnt lgkmcnt(1)
	v_mfma_f32_32x32x16_bf16 v[240:255], v[64:67], v[228:231], 0
	v_mfma_f32_32x32x16_bf16 v[240:255], v[60:63], v[232:235], v[240:255]
	v_max_i32_e32 v2, 0, v2
	v_fmac_f32_e32 v126, v239, v2
	v_max_i32_e32 v3, 0, v3
	v_fmac_f32_e32 v127, v239, v3
	v_max_i32_e32 v4, 0, v4
	v_fmac_f32_e32 v124, v239, v4
	v_max_i32_e32 v5, 0, v5
	v_fmac_f32_e32 v125, v239, v5
	v_max_i32_e32 v6, 0, v6
	v_fmac_f32_e32 v122, v239, v6
	v_max_i32_e32 v7, 0, v7
	v_fmac_f32_e32 v123, v239, v7
	v_max_i32_e32 v8, 0, v8
	v_fmac_f32_e32 v120, v239, v8
	v_max_i32_e32 v9, 0, v9
	v_fmac_f32_e32 v121, v239, v9
	v_max_i32_e32 v10, 0, v10
	v_fmac_f32_e32 v118, v239, v10
	v_max_i32_e32 v11, 0, v11
	v_fmac_f32_e32 v119, v239, v11
	v_max_i32_e32 v12, 0, v12
	v_fmac_f32_e32 v116, v239, v12
	v_max_i32_e32 v13, 0, v13
	v_fmac_f32_e32 v117, v239, v13
	v_max_i32_e32 v14, 0, v14
	v_fmac_f32_e32 v114, v239, v14
	v_max_i32_e32 v15, 0, v15
	v_fmac_f32_e32 v115, v239, v15
	v_max_i32_e32 v16, 0, v16
	v_fmac_f32_e32 v112, v239, v16
	v_max_i32_e32 v17, 0, v17
	v_fmac_f32_e32 v113, v239, v17
	v_mfma_f32_32x32x16_bf16 v[2:17], v[56:59], v[228:231], 0
	v_mfma_f32_32x32x16_bf16 v[2:17], v[52:55], v[232:235], v[2:17]
	ds_read_b128 v[228:231], v147 offset:320
	ds_read_b128 v[232:235], v147 offset:352
	v_max_i32_e32 v18, 0, v18
	v_fmac_f32_e32 v110, v239, v18
	v_max_i32_e32 v19, 0, v19
	v_fmac_f32_e32 v111, v239, v19
	v_max_i32_e32 v20, 0, v20
	v_fmac_f32_e32 v108, v239, v20
	v_max_i32_e32 v21, 0, v21
	v_fmac_f32_e32 v109, v239, v21
	v_max_i32_e32 v22, 0, v22
	v_fmac_f32_e32 v106, v239, v22
	v_max_i32_e32 v23, 0, v23
	v_fmac_f32_e32 v107, v239, v23
	v_max_i32_e32 v24, 0, v24
	v_fmac_f32_e32 v104, v239, v24
	v_max_i32_e32 v25, 0, v25
	v_fmac_f32_e32 v105, v239, v25
	v_max_i32_e32 v26, 0, v26
	v_fmac_f32_e32 v102, v239, v26
	v_max_i32_e32 v27, 0, v27
	v_fmac_f32_e32 v103, v239, v27
	v_max_i32_e32 v28, 0, v28
	v_fmac_f32_e32 v100, v239, v28
	v_max_i32_e32 v29, 0, v29
	v_fmac_f32_e32 v101, v239, v29
	v_max_i32_e32 v30, 0, v30
	v_fmac_f32_e32 v98, v239, v30
	v_max_i32_e32 v31, 0, v31
	v_fmac_f32_e32 v99, v239, v31
	v_max_i32_e32 v32, 0, v32
	v_fmac_f32_e32 v96, v239, v32
	v_max_i32_e32 v33, 0, v33
	v_fmac_f32_e32 v97, v239, v33
	ds_read_b32 v239, v153 offset:640
	s_waitcnt lgkmcnt(1)
; #define MFMA32(a, b, c) __builtin_amdgcn_mfma_f32_32x32x16_bf16((a), (b), (c), 0, 0, 0)
; DI f32x16 zero16() { f32x16 z; for (int i = 0; i < 16; i++) z[i] = 0.f; return z; }
; DI void dsa_item(const Params& P, int layer, int b, int qt, char* mb, char* smem) {
;     ...
; #pragma unroll 2
;       for (int hd = 0; hd < 8; hd++) {
;         const bf16x8 q0f = *(const bf16x8*)(sQi + r * 528 + hd * 64 + hh * 16);
;         const bf16x8 q1f = *(const bf16x8*)(sQi + r * 528 + hd * 64 + 32 + hh * 16);
;         const float w = sWi[hd * 32 + r];
;         f32x16 sa = MFMA32(kA0, q0f, zero16());
;         f32x16 sb = MFMA32(kB0, q0f, zero16());
;         sa = MFMA32(kA1, q1f, sa);
;         sb = MFMA32(kB1, q1f, sb);
; #pragma unroll
;         for (int i = 0; i < 16; i++) {
;           scA[i] += __int_as_float(max(__float_as_int(sa[i]), 0)) * w;
;           scB[i] += __int_as_float(max(__float_as_int(sb[i]), 0)) * w;
;         }
;       }
	v_mfma_f32_32x32x16_bf16 v[18:33], v[64:67], v[228:231], 0
	v_mfma_f32_32x32x16_bf16 v[18:33], v[60:63], v[232:235], v[18:33]
	v_max_i32_e32 v240, 0, v240
	v_fmac_f32_e32 v126, v238, v240
	v_max_i32_e32 v241, 0, v241
	v_fmac_f32_e32 v127, v238, v241
	v_max_i32_e32 v242, 0, v242
	v_fmac_f32_e32 v124, v238, v242
	v_max_i32_e32 v243, 0, v243
	v_fmac_f32_e32 v125, v238, v243
	v_max_i32_e32 v244, 0, v244
	v_fmac_f32_e32 v122, v238, v244
	v_max_i32_e32 v245, 0, v245
	v_fmac_f32_e32 v123, v238, v245
	v_max_i32_e32 v246, 0, v246
	v_fmac_f32_e32 v120, v238, v246
	v_max_i32_e32 v247, 0, v247
	v_fmac_f32_e32 v121, v238, v247
	v_max_i32_e32 v248, 0, v248
	v_fmac_f32_e32 v118, v238, v248
	v_max_i32_e32 v249, 0, v249
	v_fmac_f32_e32 v119, v238, v249
	v_max_i32_e32 v250, 0, v250
	v_fmac_f32_e32 v116, v238, v250
	v_max_i32_e32 v251, 0, v251
	v_fmac_f32_e32 v117, v238, v251
	v_max_i32_e32 v252, 0, v252
	v_fmac_f32_e32 v114, v238, v252
	v_max_i32_e32 v253, 0, v253
	v_fmac_f32_e32 v115, v238, v253
	v_max_i32_e32 v254, 0, v254
	v_fmac_f32_e32 v112, v238, v254
	v_max_i32_e32 v255, 0, v255
	v_fmac_f32_e32 v113, v238, v255
	v_mfma_f32_32x32x16_bf16 v[240:255], v[56:59], v[228:231], 0
	v_mfma_f32_32x32x16_bf16 v[240:255], v[52:55], v[232:235], v[240:255]
	ds_read_b128 v[228:231], v147 offset:384
	ds_read_b128 v[232:235], v147 offset:416
	v_max_i32_e32 v2, 0, v2
	v_fmac_f32_e32 v110, v238, v2
	v_max_i32_e32 v3, 0, v3
	v_fmac_f32_e32 v111, v238, v3
	v_max_i32_e32 v4, 0, v4
	v_fmac_f32_e32 v108, v238, v4
	v_max_i32_e32 v5, 0, v5
	v_fmac_f32_e32 v109, v238, v5
	v_max_i32_e32 v6, 0, v6
	v_fmac_f32_e32 v106, v238, v6
	v_max_i32_e32 v7, 0, v7
	v_fmac_f32_e32 v107, v238, v7
	v_max_i32_e32 v8, 0, v8
	v_fmac_f32_e32 v104, v238, v8
	v_max_i32_e32 v9, 0, v9
	v_fmac_f32_e32 v105, v238, v9
	v_max_i32_e32 v10, 0, v10
	v_fmac_f32_e32 v102, v238, v10
	v_max_i32_e32 v11, 0, v11
	v_fmac_f32_e32 v103, v238, v11
	v_max_i32_e32 v12, 0, v12
	v_fmac_f32_e32 v100, v238, v12
	v_max_i32_e32 v13, 0, v13
	v_fmac_f32_e32 v101, v238, v13
	v_max_i32_e32 v14, 0, v14
	v_fmac_f32_e32 v98, v238, v14
	v_max_i32_e32 v15, 0, v15
	v_fmac_f32_e32 v99, v238, v15
	v_max_i32_e32 v16, 0, v16
	v_fmac_f32_e32 v96, v238, v16
	v_max_i32_e32 v17, 0, v17
	v_fmac_f32_e32 v97, v238, v17
	ds_read_b32 v238, v153 offset:768
	s_waitcnt lgkmcnt(1)
	v_mfma_f32_32x32x16_bf16 v[2:17], v[64:67], v[228:231], 0
	v_mfma_f32_32x32x16_bf16 v[2:17], v[60:63], v[232:235], v[2:17]
	v_max_i32_e32 v18, 0, v18
	v_fmac_f32_e32 v126, v239, v18
	v_max_i32_e32 v19, 0, v19
	v_fmac_f32_e32 v127, v239, v19
	v_max_i32_e32 v20, 0, v20
	v_fmac_f32_e32 v124, v239, v20
	v_max_i32_e32 v21, 0, v21
	v_fmac_f32_e32 v125, v239, v21
	v_max_i32_e32 v22, 0, v22
	v_fmac_f32_e32 v122, v239, v22
	v_max_i32_e32 v23, 0, v23
	v_fmac_f32_e32 v123, v239, v23
	v_max_i32_e32 v24, 0, v24
	v_fmac_f32_e32 v120, v239, v24
	v_max_i32_e32 v25, 0, v25
	v_fmac_f32_e32 v121, v239, v25
	v_max_i32_e32 v26, 0, v26
	v_fmac_f32_e32 v118, v239, v26
	v_max_i32_e32 v27, 0, v27
	v_fmac_f32_e32 v119, v239, v27
	v_max_i32_e32 v28, 0, v28
	v_fmac_f32_e32 v116, v239, v28
	v_max_i32_e32 v29, 0, v29
	v_fmac_f32_e32 v117, v239, v29
	v_max_i32_e32 v30, 0, v30
	v_fmac_f32_e32 v114, v239, v30
	v_max_i32_e32 v31, 0, v31
	v_fmac_f32_e32 v115, v239, v31
	v_max_i32_e32 v32, 0, v32
	v_fmac_f32_e32 v112, v239, v32
	v_max_i32_e32 v33, 0, v33
	v_fmac_f32_e32 v113, v239, v33
	v_mfma_f32_32x32x16_bf16 v[18:33], v[56:59], v[228:231], 0
	v_mfma_f32_32x32x16_bf16 v[18:33], v[52:55], v[232:235], v[18:33]
	ds_read_b128 v[228:231], v147 offset:448
	ds_read_b128 v[232:235], v147 offset:480
	v_max_i32_e32 v240, 0, v240
	v_fmac_f32_e32 v110, v239, v240
	v_max_i32_e32 v241, 0, v241
	v_fmac_f32_e32 v111, v239, v241
	v_max_i32_e32 v242, 0, v242
	v_fmac_f32_e32 v108, v239, v242
	v_max_i32_e32 v243, 0, v243
	v_fmac_f32_e32 v109, v239, v243
	v_max_i32_e32 v244, 0, v244
	v_fmac_f32_e32 v106, v239, v244
	v_max_i32_e32 v245, 0, v245
	v_fmac_f32_e32 v107, v239, v245
	v_max_i32_e32 v246, 0, v246
	v_fmac_f32_e32 v104, v239, v246
	v_max_i32_e32 v247, 0, v247
	v_fmac_f32_e32 v105, v239, v247
	v_max_i32_e32 v248, 0, v248
	v_fmac_f32_e32 v102, v239, v248
	v_max_i32_e32 v249, 0, v249
	v_fmac_f32_e32 v103, v239, v249
	v_max_i32_e32 v250, 0, v250
	v_fmac_f32_e32 v100, v239, v250
	v_max_i32_e32 v251, 0, v251
	v_fmac_f32_e32 v101, v239, v251
	v_max_i32_e32 v252, 0, v252
	v_fmac_f32_e32 v98, v239, v252
	v_max_i32_e32 v253, 0, v253
	v_fmac_f32_e32 v99, v239, v253
	v_max_i32_e32 v254, 0, v254
	v_fmac_f32_e32 v96, v239, v254
	v_max_i32_e32 v255, 0, v255
	v_fmac_f32_e32 v97, v239, v255
	ds_read_b32 v239, v153 offset:896
	s_waitcnt lgkmcnt(1)
; #define MFMA32(a, b, c) __builtin_amdgcn_mfma_f32_32x32x16_bf16((a), (b), (c), 0, 0, 0)
; DI f32x16 zero16() { f32x16 z; for (int i = 0; i < 16; i++) z[i] = 0.f; return z; }
; DI void dsa_item(const Params& P, int layer, int b, int qt, char* mb, char* smem) {
;     ...
; #pragma unroll 2
;       for (int hd = 0; hd < 8; hd++) {
;         const bf16x8 q0f = *(const bf16x8*)(sQi + r * 528 + hd * 64 + hh * 16);
;         const bf16x8 q1f = *(const bf16x8*)(sQi + r * 528 + hd * 64 + 32 + hh * 16);
;         const float w = sWi[hd * 32 + r];
;         f32x16 sa = MFMA32(kA0, q0f, zero16());
;         f32x16 sb = MFMA32(kB0, q0f, zero16());
;         sa = MFMA32(kA1, q1f, sa);
;         sb = MFMA32(kB1, q1f, sb);
; #pragma unroll
;         for (int i = 0; i < 16; i++) {
;           scA[i] += __int_as_float(max(__float_as_int(sa[i]), 0)) * w;
;           scB[i] += __int_as_float(max(__float_as_int(sb[i]), 0)) * w;
;         }
;       }
;       elems(scA, kt, (kt == qt) ? qp : 0x7fffffff);
;       if (kt + 4 < nk32) elems(scB, kt + 4, (kt + 4 == qt) ? qp : 0x7fffffff);
	v_mfma_f32_32x32x16_bf16 v[240:255], v[64:67], v[228:231], 0
	v_mfma_f32_32x32x16_bf16 v[240:255], v[60:63], v[232:235], v[240:255]
	v_max_i32_e32 v2, 0, v2
	v_fmac_f32_e32 v126, v238, v2
	v_max_i32_e32 v3, 0, v3
	v_fmac_f32_e32 v127, v238, v3
	v_max_i32_e32 v4, 0, v4
	v_fmac_f32_e32 v124, v238, v4
	v_max_i32_e32 v5, 0, v5
	v_fmac_f32_e32 v125, v238, v5
	v_max_i32_e32 v6, 0, v6
	v_fmac_f32_e32 v122, v238, v6
	v_max_i32_e32 v7, 0, v7
	v_fmac_f32_e32 v123, v238, v7
	v_max_i32_e32 v8, 0, v8
	v_fmac_f32_e32 v120, v238, v8
	v_max_i32_e32 v9, 0, v9
	v_fmac_f32_e32 v121, v238, v9
	v_max_i32_e32 v10, 0, v10
	v_fmac_f32_e32 v118, v238, v10
	v_max_i32_e32 v11, 0, v11
	v_fmac_f32_e32 v119, v238, v11
	v_max_i32_e32 v12, 0, v12
	v_fmac_f32_e32 v116, v238, v12
	v_max_i32_e32 v13, 0, v13
	v_fmac_f32_e32 v117, v238, v13
	v_max_i32_e32 v14, 0, v14
	v_fmac_f32_e32 v114, v238, v14
	v_max_i32_e32 v15, 0, v15
	v_fmac_f32_e32 v115, v238, v15
	v_max_i32_e32 v16, 0, v16
	v_fmac_f32_e32 v112, v238, v16
	v_max_i32_e32 v17, 0, v17
	v_fmac_f32_e32 v113, v238, v17
	v_mfma_f32_32x32x16_bf16 v[2:17], v[56:59], v[228:231], 0
	v_mfma_f32_32x32x16_bf16 v[2:17], v[52:55], v[232:235], v[2:17]
	v_max_i32_e32 v18, 0, v18
	v_fmac_f32_e32 v110, v238, v18
	v_max_i32_e32 v19, 0, v19
	v_fmac_f32_e32 v111, v238, v19
	v_max_i32_e32 v20, 0, v20
	v_fmac_f32_e32 v108, v238, v20
	v_max_i32_e32 v21, 0, v21
	v_fmac_f32_e32 v109, v238, v21
	v_max_i32_e32 v22, 0, v22
	v_fmac_f32_e32 v106, v238, v22
	v_max_i32_e32 v23, 0, v23
	v_fmac_f32_e32 v107, v238, v23
	v_max_i32_e32 v24, 0, v24
	v_fmac_f32_e32 v104, v238, v24
	v_max_i32_e32 v25, 0, v25
	v_fmac_f32_e32 v105, v238, v25
	v_max_i32_e32 v26, 0, v26
	v_fmac_f32_e32 v102, v238, v26
	v_max_i32_e32 v27, 0, v27
	v_fmac_f32_e32 v103, v238, v27
	v_max_i32_e32 v28, 0, v28
	v_fmac_f32_e32 v100, v238, v28
	v_max_i32_e32 v29, 0, v29
	v_fmac_f32_e32 v101, v238, v29
	v_max_i32_e32 v30, 0, v30
	v_fmac_f32_e32 v98, v238, v30
	v_max_i32_e32 v31, 0, v31
	v_fmac_f32_e32 v99, v238, v31
	v_max_i32_e32 v32, 0, v32
	v_fmac_f32_e32 v96, v238, v32
	v_max_i32_e32 v33, 0, v33
	v_fmac_f32_e32 v97, v238, v33
	s_waitcnt lgkmcnt(0)
	v_max_i32_e32 v240, 0, v240
	v_fmac_f32_e32 v126, v239, v240
	v_max_i32_e32 v241, 0, v241
	v_fmac_f32_e32 v127, v239, v241
	v_max_i32_e32 v242, 0, v242
	v_fmac_f32_e32 v124, v239, v242
	v_max_i32_e32 v243, 0, v243
	v_fmac_f32_e32 v125, v239, v243
	v_max_i32_e32 v244, 0, v244
	v_fmac_f32_e32 v122, v239, v244
	v_max_i32_e32 v245, 0, v245
	v_fmac_f32_e32 v123, v239, v245
	v_max_i32_e32 v246, 0, v246
	v_fmac_f32_e32 v120, v239, v246
	v_max_i32_e32 v247, 0, v247
	v_fmac_f32_e32 v121, v239, v247
	v_max_i32_e32 v248, 0, v248
	v_fmac_f32_e32 v118, v239, v248
	v_max_i32_e32 v249, 0, v249
	v_fmac_f32_e32 v119, v239, v249
	v_max_i32_e32 v250, 0, v250
	v_fmac_f32_e32 v116, v239, v250
	v_max_i32_e32 v251, 0, v251
	v_fmac_f32_e32 v117, v239, v251
	v_max_i32_e32 v252, 0, v252
	v_fmac_f32_e32 v114, v239, v252
	v_max_i32_e32 v253, 0, v253
	v_fmac_f32_e32 v115, v239, v253
	v_max_i32_e32 v254, 0, v254
	v_fmac_f32_e32 v112, v239, v254
	v_max_i32_e32 v255, 0, v255
	v_fmac_f32_e32 v113, v239, v255
	v_max_i32_e32 v2, 0, v2
	v_fmac_f32_e32 v110, v239, v2
	v_max_i32_e32 v3, 0, v3
	v_fmac_f32_e32 v111, v239, v3
	v_max_i32_e32 v4, 0, v4
	v_fmac_f32_e32 v108, v239, v4
	v_max_i32_e32 v5, 0, v5
	v_fmac_f32_e32 v109, v239, v5
	v_max_i32_e32 v6, 0, v6
	v_fmac_f32_e32 v106, v239, v6
	v_max_i32_e32 v7, 0, v7
	v_fmac_f32_e32 v107, v239, v7
	v_max_i32_e32 v8, 0, v8
	v_fmac_f32_e32 v104, v239, v8
	v_max_i32_e32 v9, 0, v9
	v_fmac_f32_e32 v105, v239, v9
	v_max_i32_e32 v10, 0, v10
	v_fmac_f32_e32 v102, v239, v10
	v_max_i32_e32 v11, 0, v11
	v_fmac_f32_e32 v103, v239, v11
	v_max_i32_e32 v12, 0, v12
	v_fmac_f32_e32 v100, v239, v12
	v_max_i32_e32 v13, 0, v13
	v_fmac_f32_e32 v101, v239, v13
	v_max_i32_e32 v14, 0, v14
	v_fmac_f32_e32 v98, v239, v14
	v_max_i32_e32 v15, 0, v15
	v_fmac_f32_e32 v99, v239, v15
	v_max_i32_e32 v16, 0, v16
	v_fmac_f32_e32 v96, v239, v16
	v_max_i32_e32 v17, 0, v17
	v_fmac_f32_e32 v97, v239, v17
	s_movk_i32 s0, 0x200
	v_cmp_eq_u32_e32 vcc, s60, v151
	v_lshlrev_b32_e32 v31, 5, v151
	s_nop 0
	v_cndmask_b32_e32 v30, v201, v137, vcc
	s_and_b64 vcc, exec, s[82:83]
	s_cbranch_vccz .LBB0_7249
	s_andn2_b64 vcc, exec, s[78:79]
	s_mov_b64 s[0:1], -1
	s_cbranch_vccnz .LBB0_7241
; DI int crow(int i, int hh) { return (i & 3) + 8 * (i >> 2) + 4 * hh; }
; DI unsigned sortkey(float f) { const unsigned u = __float_as_uint(f + 0.f); return u ^ (((unsigned)((int)u >> 31)) | 0x80000000u); }
; DI void dsa_item(const Params& P, int layer, int b, int qt, char* mb, char* smem) {
;     ...
;       } else if (pass < 4) {
;         const int sh = 24 - 8 * pass;
; #pragma unroll
;         for (int i = 0; i < 16; i++) {
;           const int kp = kt * 32 + crow(i, hh);
;           const unsigned key = sortkey(sc[i]);
;           if ((key >> (sh + 8)) == pref && kp <= lim) atomicAdd(&hist[r * 257 + ((key >> sh) & 255u)], 1u);
;         }
	v_add_f32_e32 v2, 0, v126
	v_ashrrev_i32_e32 v3, 31, v2
	v_bitop3_b32 v3, v3, v2, s97 bitop3:0x36
	v_lshrrev_b32_e32 v2, s56, v3
	v_cmp_eq_u32_e32 vcc, v2, v94
	v_or_b32_e32 v2, v31, v134
	v_cmp_le_i32_e64 s[0:1], v2, v30
	s_and_b64 s[18:19], vcc, s[0:1]
	s_and_saveexec_b64 s[0:1], s[18:19]
	v_bfe_u32 v3, v3, s67, 8
	v_lshl_add_u32 v3, v3, 2, v144
	ds_add_u32 v3, v192
	s_or_b64 exec, exec, s[0:1]
	v_add_f32_e32 v3, 0, v127
	v_ashrrev_i32_e32 v4, 31, v3
	v_bitop3_b32 v3, v4, v3, s97 bitop3:0x36
	v_lshrrev_b32_e32 v4, s56, v3
	v_cmp_eq_u32_e32 vcc, v4, v94
	v_cmp_lt_i32_e64 s[0:1], v2, v30
	s_and_b64 s[18:19], vcc, s[0:1]
	s_and_saveexec_b64 s[0:1], s[18:19]
	v_bfe_u32 v2, v3, s67, 8
	v_lshl_add_u32 v2, v2, 2, v144
	ds_add_u32 v2, v192
	s_or_b64 exec, exec, s[0:1]
	v_add_f32_e32 v2, 0, v124
	v_ashrrev_i32_e32 v3, 31, v2
	v_bitop3_b32 v2, v3, v2, s97 bitop3:0x36
	v_lshrrev_b32_e32 v3, s56, v2
	v_cmp_eq_u32_e32 vcc, v3, v94
	v_or_b32_e32 v3, v31, v74
	v_cmp_le_i32_e64 s[0:1], v3, v30
	s_and_b64 s[18:19], vcc, s[0:1]
	s_and_saveexec_b64 s[0:1], s[18:19]
	v_bfe_u32 v2, v2, s67, 8
	v_lshl_add_u32 v2, v2, 2, v144
	ds_add_u32 v2, v192
	s_or_b64 exec, exec, s[0:1]
	v_add_f32_e32 v2, 0, v125
	v_ashrrev_i32_e32 v3, 31, v2
	v_bitop3_b32 v2, v3, v2, s97 bitop3:0x36
	v_lshrrev_b32_e32 v3, s56, v2
	v_cmp_eq_u32_e32 vcc, v3, v94
	v_or_b32_e32 v3, v31, v1
	v_cmp_le_i32_e64 s[0:1], v3, v30
	s_and_b64 s[18:19], vcc, s[0:1]
	s_and_saveexec_b64 s[0:1], s[18:19]
	v_bfe_u32 v2, v2, s67, 8
	v_lshl_add_u32 v2, v2, 2, v144
	ds_add_u32 v2, v192
	s_or_b64 exec, exec, s[0:1]
	v_add_f32_e32 v2, 0, v122
	v_ashrrev_i32_e32 v3, 31, v2
	v_bitop3_b32 v2, v3, v2, s97 bitop3:0x36
	v_lshrrev_b32_e32 v3, s56, v2
	v_cmp_eq_u32_e32 vcc, v3, v94
	v_or_b32_e32 v3, v31, v76
	v_cmp_le_i32_e64 s[0:1], v3, v30
	s_and_b64 s[18:19], vcc, s[0:1]
	s_and_saveexec_b64 s[0:1], s[18:19]
	v_bfe_u32 v2, v2, s67, 8
	v_lshl_add_u32 v2, v2, 2, v144
	ds_add_u32 v2, v192
	s_or_b64 exec, exec, s[0:1]
	v_add_f32_e32 v2, 0, v123
	v_ashrrev_i32_e32 v3, 31, v2
	v_bitop3_b32 v2, v3, v2, s97 bitop3:0x36
	v_lshrrev_b32_e32 v3, s56, v2
	v_cmp_eq_u32_e32 vcc, v3, v94
	v_or_b32_e32 v3, v31, v69
	v_cmp_le_i32_e64 s[0:1], v3, v30
	s_and_b64 s[18:19], vcc, s[0:1]
	s_and_saveexec_b64 s[0:1], s[18:19]
	v_bfe_u32 v2, v2, s67, 8
	v_lshl_add_u32 v2, v2, 2, v144
	ds_add_u32 v2, v192
	s_or_b64 exec, exec, s[0:1]
	v_add_f32_e32 v2, 0, v120
	v_ashrrev_i32_e32 v3, 31, v2
	v_bitop3_b32 v2, v3, v2, s97 bitop3:0x36
	v_lshrrev_b32_e32 v3, s56, v2
	v_cmp_eq_u32_e32 vcc, v3, v94
	v_or_b32_e32 v3, v31, v78
	v_cmp_le_i32_e64 s[0:1], v3, v30
	s_and_b64 s[18:19], vcc, s[0:1]
	s_and_saveexec_b64 s[0:1], s[18:19]
	v_bfe_u32 v2, v2, s67, 8
	v_lshl_add_u32 v2, v2, 2, v144
	ds_add_u32 v2, v192
	s_or_b64 exec, exec, s[0:1]
	v_add_f32_e32 v2, 0, v121
	v_ashrrev_i32_e32 v3, 31, v2
	v_bitop3_b32 v2, v3, v2, s97 bitop3:0x36
	v_lshrrev_b32_e32 v3, s56, v2
	v_cmp_eq_u32_e32 vcc, v3, v94
	v_or_b32_e32 v3, v31, v71
	v_cmp_le_i32_e64 s[0:1], v3, v30
	s_and_b64 s[18:19], vcc, s[0:1]
	s_and_saveexec_b64 s[0:1], s[18:19]
	v_bfe_u32 v2, v2, s67, 8
	v_lshl_add_u32 v2, v2, 2, v144
	ds_add_u32 v2, v192
	s_or_b64 exec, exec, s[0:1]
	v_add_f32_e32 v2, 0, v118
	v_ashrrev_i32_e32 v3, 31, v2
	v_bitop3_b32 v2, v3, v2, s97 bitop3:0x36
	v_lshrrev_b32_e32 v3, s56, v2
	v_cmp_eq_u32_e32 vcc, v3, v94
	v_or_b32_e32 v3, v31, v80
	v_cmp_le_i32_e64 s[0:1], v3, v30
	s_and_b64 s[18:19], vcc, s[0:1]
	s_and_saveexec_b64 s[0:1], s[18:19]
	v_bfe_u32 v2, v2, s67, 8
	v_lshl_add_u32 v2, v2, 2, v144
	ds_add_u32 v2, v192
	s_or_b64 exec, exec, s[0:1]
	v_add_f32_e32 v2, 0, v119
	v_ashrrev_i32_e32 v3, 31, v2
	v_bitop3_b32 v2, v3, v2, s97 bitop3:0x36
	v_lshrrev_b32_e32 v3, s56, v2
	v_cmp_eq_u32_e32 vcc, v3, v94
	v_or_b32_e32 v3, v31, v75
	v_cmp_le_i32_e64 s[0:1], v3, v30
	s_and_b64 s[18:19], vcc, s[0:1]
	s_and_saveexec_b64 s[0:1], s[18:19]
	v_bfe_u32 v2, v2, s67, 8
	v_lshl_add_u32 v2, v2, 2, v144
	ds_add_u32 v2, v192
	s_or_b64 exec, exec, s[0:1]
	v_add_f32_e32 v2, 0, v116
	v_ashrrev_i32_e32 v3, 31, v2
	v_bitop3_b32 v2, v3, v2, s97 bitop3:0x36
	v_lshrrev_b32_e32 v3, s56, v2
	v_cmp_eq_u32_e32 vcc, v3, v94
	v_or_b32_e32 v3, v31, v82
	v_cmp_le_i32_e64 s[0:1], v3, v30
	s_and_b64 s[18:19], vcc, s[0:1]
	s_and_saveexec_b64 s[0:1], s[18:19]
	v_bfe_u32 v2, v2, s67, 8
	v_lshl_add_u32 v2, v2, 2, v144
	ds_add_u32 v2, v192
	s_or_b64 exec, exec, s[0:1]
	v_add_f32_e32 v2, 0, v117
	v_ashrrev_i32_e32 v3, 31, v2
	v_bitop3_b32 v2, v3, v2, s97 bitop3:0x36
	v_lshrrev_b32_e32 v3, s56, v2
	v_cmp_eq_u32_e32 vcc, v3, v94
	v_or_b32_e32 v3, v31, v77
	v_cmp_le_i32_e64 s[0:1], v3, v30
	s_and_b64 s[18:19], vcc, s[0:1]
	s_and_saveexec_b64 s[0:1], s[18:19]
	v_bfe_u32 v2, v2, s67, 8
	v_lshl_add_u32 v2, v2, 2, v144
	ds_add_u32 v2, v192
	s_or_b64 exec, exec, s[0:1]
	v_add_f32_e32 v2, 0, v114
	v_ashrrev_i32_e32 v3, 31, v2
	v_bitop3_b32 v2, v3, v2, s97 bitop3:0x36
	v_lshrrev_b32_e32 v3, s56, v2
	v_cmp_eq_u32_e32 vcc, v3, v94
	v_or_b32_e32 v3, v31, v84
	v_cmp_le_i32_e64 s[0:1], v3, v30
	s_and_b64 s[18:19], vcc, s[0:1]
	s_and_saveexec_b64 s[0:1], s[18:19]
	v_bfe_u32 v2, v2, s67, 8
	v_lshl_add_u32 v2, v2, 2, v144
	ds_add_u32 v2, v192
	s_or_b64 exec, exec, s[0:1]
	v_add_f32_e32 v2, 0, v115
	v_ashrrev_i32_e32 v3, 31, v2
	v_bitop3_b32 v2, v3, v2, s97 bitop3:0x36
	v_lshrrev_b32_e32 v3, s56, v2
	v_cmp_eq_u32_e32 vcc, v3, v94
	v_or_b32_e32 v3, v31, v79
	v_cmp_le_i32_e64 s[0:1], v3, v30
	s_and_b64 s[18:19], vcc, s[0:1]
	s_and_saveexec_b64 s[0:1], s[18:19]
	v_bfe_u32 v2, v2, s67, 8
	v_lshl_add_u32 v2, v2, 2, v144
	ds_add_u32 v2, v192
	s_or_b64 exec, exec, s[0:1]
	v_add_f32_e32 v2, 0, v112
	v_ashrrev_i32_e32 v3, 31, v2
	v_bitop3_b32 v2, v3, v2, s97 bitop3:0x36
	v_lshrrev_b32_e32 v3, s56, v2
	v_cmp_eq_u32_e32 vcc, v3, v94
	v_or_b32_e32 v3, v31, v86
	v_cmp_le_i32_e64 s[0:1], v3, v30
	s_and_b64 s[18:19], vcc, s[0:1]
	s_and_saveexec_b64 s[0:1], s[18:19]
	v_bfe_u32 v2, v2, s67, 8
	v_lshl_add_u32 v2, v2, 2, v144
	ds_add_u32 v2, v192
	s_or_b64 exec, exec, s[0:1]
	v_add_f32_e32 v2, 0, v113
	v_ashrrev_i32_e32 v3, 31, v2
	v_bitop3_b32 v2, v3, v2, s97 bitop3:0x36
	v_lshrrev_b32_e32 v3, s56, v2
	v_cmp_eq_u32_e32 vcc, v3, v94
	v_or_b32_e32 v3, v31, v81
	v_cmp_le_i32_e64 s[0:1], v3, v30
	s_and_b64 s[18:19], vcc, s[0:1]
	s_and_saveexec_b64 s[0:1], s[18:19]
	v_bfe_u32 v2, v2, s67, 8
	v_lshl_add_u32 v2, v2, 2, v144
	ds_add_u32 v2, v192
	s_or_b64 exec, exec, s[0:1]
	s_mov_b64 s[0:1], 0

; DI void dsa_item(const Params& P, int layer, int b, int qt, char* mb, char* smem) {
;     ...
;     __syncthreads();
;     float sc[4][4];
; #pragma unroll
;     for (int rd = 0; rd < 4; rd++) {
;       const int jj = rd * 64 + lane;
;       const bool valid = jj < n;
;       const int kidx = valid ? (int)sidx[qq * 256 + jj] : 0;
;       const int dist = min(max(qpos - kidx, 0), 128);
;       const float4 d = *(const float4*)(myP + jj * 4);
;       sc[rd][0] = valid ? d.x * 0.125f + sbias[0 * 129 + dist] : -INFINITY;
;       sc[rd][1] = valid ? d.y * 0.125f + sbias[1 * 129 + dist] : -INFINITY;
;       sc[rd][2] = valid ? d.z * 0.125f + sbias[2 * 129 + dist] : -INFINITY;
;       sc[rd][3] = valid ? d.w * 0.125f + sbias[3 * 129 + dist] : -INFINITY;
;     }
.LBB0_7997:
	s_nop 3
	v_lshlrev_b32_e32 v3, 8, v52
	v_cmp_gt_i32_e32 vcc, v53, v205
	v_mov_b32_e32 v2, 0
	v_lshl_add_u32 v12, v3, 1, v215
	s_waitcnt lgkmcnt(0)
	s_and_saveexec_b64 s[12:13], vcc
	ds_read_u16 v2, v12 offset:32896
	s_or_b64 exec, exec, s[12:13]
	ds_read2_b32 v[4:5], v220 offset0:1 offset1:2
	ds_read_b32 v6, v220 offset:12
	v_add_u32_e32 v156, s59, v52
	s_waitcnt lgkmcnt(2)
	v_sub_u32_e32 v2, v156, v2
	v_med3_i32 v3, v2, 0, v204
	v_mov_b32_e32 v2, 0xff800000
	v_lshl_add_u32 v7, v3, 2, 0
	v_mov_b32_e32 v10, 0xff800000
	s_and_saveexec_b64 s[12:13], vcc
	s_cbranch_execz .LBB0_8055
	ds_read_b32 v3, v220
	ds_read_b32 v10, v7 offset:50304
	s_waitcnt lgkmcnt(0)
	v_fmac_f32_e32 v10, 0x3e000000, v3
	s_or_b64 exec, exec, s[12:13]
	v_mov_b32_e32 v3, 0xff800000
	s_and_saveexec_b64 s[12:13], vcc
	s_cbranch_execnz .LBB0_8056

; DI char* WS(const Params& P) { return P.ws + opaque0(); }
; DI void da_item(const Params& P, int layer, int b, int h, int qt, char* mb, char* smem) {
;     ...
;   __syncthreads();
;   if (tid < 129) sbias[tid] = ((const float*)(WS(P) + OFF_BIAS))[h * 129 + tid] * LOG2E_;
;   __syncthreads();
; DI void phase_mix1(const Params& P, int layer, int bid, int nb, char* smem) {
;     ...
;   for (int j = 0;; j++) {
;     const int idx = (j & 1) ? (j * nb + (nb - 1 - bid)) : (j * nb + bid);
;     if (j * nb >= 2048) break;
;     if (idx >= 2048) continue;
;     const int qt = 63 - (idx >> 5), bh = idx & 31;
;     da_item(P, layer, bh >> 2, bh & 3, qt, mb, smem);
.LBB0_8070:
	s_waitcnt vmcnt(0) lgkmcnt(0)
	s_barrier
	v_readlane_b32 s4, v237, 9
	v_readlane_b32 s5, v237, 10
	s_mov_b64 s[22:23], exec
	s_and_b64 s[4:5], s[22:23], s[4:5]
	s_mov_b64 exec, s[4:5]
	s_cbranch_execz .Lq_da1_skip
	v_readlane_b32 s4, v237, 0
	v_readlane_b32 s5, v237, 1
	s_add_u32 s4, s4, 0x55892c0
	s_addc_u32 s5, s5, 0
	v_mov_b32_e32 v238, 0
	v_mov_b32_e32 v239, 1
	global_atomic_add v239, v238, v239, s[4:5] sc0
	v_mov_b32_e32 v238, 0x11ff8
	s_waitcnt vmcnt(0)
	ds_write_b32 v238, v239
.Lq_da1_skip:
	s_mov_b64 exec, s[22:23]
	s_waitcnt lgkmcnt(0)
	s_barrier
	v_mov_b32_e32 v238, 0x11ff8
	ds_read_b32 v238, v238
	s_waitcnt lgkmcnt(0)
	s_nop 0
	v_readfirstlane_b32 s10, v238
	s_mov_b32 s28, s10
	s_mov_b32 s39, 0
	s_cmpk_gt_i32 s10, 0x7ff
	s_mov_b32 s24, 8
	s_cbranch_scc1 .LBB0_8093
	v_mov_b32_e32 v3, v202
	s_and_b32 s24, s10, 3
	v_mov_b32_e32 v1, v202
	s_mov_b64 s[4:5], 0
	v_cmp_gt_i32_e32 vcc, s3, v3
	s_waitcnt vmcnt(0) lgkmcnt(0)
	s_barrier
	s_and_saveexec_b64 s[22:23], vcc
	s_cbranch_execz .LBB0_8074
	s_mov_b64 s[26:27], 0
	v_readlane_b32 s30, v237, 0
	s_mul_i32 s25, s24, 0x81
	v_readlane_b32 s31, v237, 1
	s_add_u32 s26, s30, s26
	v_add_u32_e32 v4, s25, v3
	s_addc_u32 s27, s31, s27
	v_ashrrev_i32_e32 v5, 31, v4
	v_lshl_add_u64 v[4:5], v[4:5], 2, s[26:27]
	v_add_co_u32_e32 v4, vcc, 0x5588000, v4
	s_nop 1
	v_addc_co_u32_e32 v5, vcc, 0, v5, vcc
	global_load_dword v4, v[4:5], off offset:256
	v_lshl_add_u32 v5, v3, 2, 0
	s_waitcnt vmcnt(0)
	v_mul_f32_e32 v4, 0x3fb8aa3b, v4
	ds_write_b32 v5, v4 offset:53248
